# GEMM epilogue outputs (XY, ACT) stored write-through (sc0 sc1) so the seam barrier has less dirty L2 to write back
# speedup vs baseline: 1.0032x; 1.0032x over previous
.Lupc_6:
	v_pk_mul_f32 v[144:145], v[242:243], s[6:7] op_sel_hi:[1,0]
	v_pk_mul_f32 v[246:247], v[244:245], s[6:7] op_sel_hi:[1,0]
	v_exp_f32_e32 v144, v144
	v_exp_f32_e32 v145, v145
	v_exp_f32_e32 v246, v246
	v_exp_f32_e32 v247, v247
	v_add_f32_e32 v144, 1.0, v144
	v_add_f32_e32 v145, 1.0, v145
	v_add_f32_e32 v246, 1.0, v246
	v_add_f32_e32 v247, 1.0, v247
	v_rcp_f32_e32 v144, v144
	v_rcp_f32_e32 v145, v145
	v_rcp_f32_e32 v246, v246
	v_rcp_f32_e32 v247, v247
	s_nop 0
	v_pk_mul_f32 v[144:145], v[242:243], v[144:145]
	v_pk_mul_f32 v[246:247], v[244:245], v[246:247]
	v_pk_mul_f32 v[144:145], v[238:239], v[144:145]
	v_pk_mul_f32 v[246:247], v[240:241], v[246:247]
	v_cvt_pk_bf16_f32 v134, v144, v145
	v_cvt_pk_bf16_f32 v135, v246, v247
	s_add_u32 s26, s94, 0x1e4000
	s_addc_u32 s27, s95, 0
	global_store_dwordx4 v217, v[132:135], s[26:27] sc0 sc1
	v_pk_fma_f32 v[238:239], v[146:147], v[14:15], v[102:103]
	v_pk_fma_f32 v[240:241], v[148:149], v[16:17], v[104:105]
	v_pk_fma_f32 v[242:243], v[114:115], v[10:11], v[98:99]
	v_pk_fma_f32 v[244:245], v[116:117], v[12:13], v[100:101]
	v_fmac_f32_dpp v238, v14, v158 row_shr:1 row_mask:0xf bank_mask:0xf
	v_fmac_f32_dpp v239, v15, v159 row_shr:1 row_mask:0xf bank_mask:0xf
	v_fmac_f32_dpp v240, v16, v160 row_shr:1 row_mask:0xf bank_mask:0xf
	v_fmac_f32_dpp v241, v17, v161 row_shr:1 row_mask:0xf bank_mask:0xf
	v_fmac_f32_dpp v242, v10, v154 row_shr:1 row_mask:0xf bank_mask:0xf
	v_fmac_f32_dpp v243, v11, v155 row_shr:1 row_mask:0xf bank_mask:0xf
	v_fmac_f32_dpp v244, v12, v156 row_shr:1 row_mask:0xf bank_mask:0xf
	v_fmac_f32_dpp v245, v13, v157 row_shr:1 row_mask:0xf bank_mask:0xf
	v_fmac_f32_dpp v238, v14, v110 row_shl:1 row_mask:0xf bank_mask:0xf
	v_fmac_f32_dpp v239, v15, v111 row_shl:1 row_mask:0xf bank_mask:0xf
	v_fmac_f32_dpp v240, v16, v112 row_shl:1 row_mask:0xf bank_mask:0xf
	v_fmac_f32_dpp v241, v17, v113 row_shl:1 row_mask:0xf bank_mask:0xf
	v_fmac_f32_dpp v242, v10, v106 row_shl:1 row_mask:0xf bank_mask:0xf
	v_fmac_f32_dpp v243, v11, v107 row_shl:1 row_mask:0xf bank_mask:0xf
	v_fmac_f32_dpp v244, v12, v108 row_shl:1 row_mask:0xf bank_mask:0xf
	v_fmac_f32_dpp v245, v13, v109 row_shl:1 row_mask:0xf bank_mask:0xf
	v_cndmask_b32_e64 v144, 0, v158, s[38:39]
	v_cndmask_b32_e64 v145, 0, v159, s[38:39]
	v_cndmask_b32_e64 v246, 0, v160, s[38:39]
	v_cndmask_b32_e64 v247, 0, v161, s[38:39]
	v_fmac_f32_dpp v238, v22, v144 row_ror:1 row_mask:0xf bank_mask:0xf
	v_fmac_f32_dpp v239, v23, v145 row_ror:1 row_mask:0xf bank_mask:0xf
	v_fmac_f32_dpp v240, v24, v246 row_ror:1 row_mask:0xf bank_mask:0xf
	v_fmac_f32_dpp v241, v25, v247 row_ror:1 row_mask:0xf bank_mask:0xf
	v_cndmask_b32_e64 v144, 0, v154, s[38:39]
	v_cndmask_b32_e64 v145, 0, v155, s[38:39]
	v_cndmask_b32_e64 v246, 0, v156, s[38:39]
	v_cndmask_b32_e64 v247, 0, v157, s[38:39]
	v_fmac_f32_dpp v242, v18, v144 row_ror:1 row_mask:0xf bank_mask:0xf
	v_fmac_f32_dpp v243, v19, v145 row_ror:1 row_mask:0xf bank_mask:0xf
	v_fmac_f32_dpp v244, v20, v246 row_ror:1 row_mask:0xf bank_mask:0xf
	v_fmac_f32_dpp v245, v21, v247 row_ror:1 row_mask:0xf bank_mask:0xf
	v_cndmask_b32_e64 v144, 0, v110, s[40:41]
	v_cndmask_b32_e64 v145, 0, v111, s[40:41]
	v_cndmask_b32_e64 v246, 0, v112, s[40:41]
	v_cndmask_b32_e64 v247, 0, v113, s[40:41]
	v_fmac_f32_dpp v238, v2, v144 row_ror:15 row_mask:0xf bank_mask:0xf
	v_fmac_f32_dpp v239, v3, v145 row_ror:15 row_mask:0xf bank_mask:0xf
	v_fmac_f32_dpp v240, v4, v246 row_ror:15 row_mask:0xf bank_mask:0xf
	v_fmac_f32_dpp v241, v5, v247 row_ror:15 row_mask:0xf bank_mask:0xf
	v_cndmask_b32_e64 v144, 0, v106, s[40:41]
	v_cndmask_b32_e64 v145, 0, v107, s[40:41]
	v_cndmask_b32_e64 v246, 0, v108, s[40:41]
	v_cndmask_b32_e64 v247, 0, v109, s[40:41]
	v_fmac_f32_dpp v242, v6, v144 row_ror:15 row_mask:0xf bank_mask:0xf
	v_fmac_f32_dpp v243, v7, v145 row_ror:15 row_mask:0xf bank_mask:0xf
	v_fmac_f32_dpp v244, v8, v246 row_ror:15 row_mask:0xf bank_mask:0xf
	v_fmac_f32_dpp v245, v9, v247 row_ror:15 row_mask:0xf bank_mask:0xf
	v_pk_mul_f32 v[144:145], v[242:243], s[6:7] op_sel_hi:[1,0]
	v_pk_mul_f32 v[246:247], v[244:245], s[6:7] op_sel_hi:[1,0]
	v_exp_f32_e32 v144, v144
	v_exp_f32_e32 v145, v145
	v_exp_f32_e32 v246, v246
	v_exp_f32_e32 v247, v247
	v_add_f32_e32 v144, 1.0, v144
	v_add_f32_e32 v145, 1.0, v145
	v_add_f32_e32 v246, 1.0, v246
	v_add_f32_e32 v247, 1.0, v247
	v_rcp_f32_e32 v144, v144
	v_rcp_f32_e32 v145, v145
	v_rcp_f32_e32 v246, v246
	v_rcp_f32_e32 v247, v247
	s_nop 0
	v_pk_mul_f32 v[144:145], v[242:243], v[144:145]
	v_pk_mul_f32 v[246:247], v[244:245], v[246:247]
	v_pk_mul_f32 v[144:145], v[238:239], v[144:145]
	v_pk_mul_f32 v[246:247], v[240:241], v[246:247]
	v_cvt_pk_bf16_f32 v132, v144, v145
	v_cvt_pk_bf16_f32 v133, v246, v247
	s_add_u32 s26, s94, 0x1b8000
	s_addc_u32 s27, s95, 0
	global_store_dwordx4 v217, v[130:133], s[26:27] sc0 sc1
	v_pk_fma_f32 v[238:239], v[146:147], v[22:23], v[102:103]
	v_pk_fma_f32 v[240:241], v[148:149], v[24:25], v[104:105]
	v_pk_fma_f32 v[242:243], v[114:115], v[18:19], v[98:99]
	v_pk_fma_f32 v[244:245], v[116:117], v[20:21], v[100:101]
	v_fmac_f32_dpp v238, v22, v158 row_shr:1 row_mask:0xf bank_mask:0xf
	v_fmac_f32_dpp v239, v23, v159 row_shr:1 row_mask:0xf bank_mask:0xf
	v_fmac_f32_dpp v240, v24, v160 row_shr:1 row_mask:0xf bank_mask:0xf
	v_fmac_f32_dpp v241, v25, v161 row_shr:1 row_mask:0xf bank_mask:0xf
	v_fmac_f32_dpp v242, v18, v154 row_shr:1 row_mask:0xf bank_mask:0xf
	v_fmac_f32_dpp v243, v19, v155 row_shr:1 row_mask:0xf bank_mask:0xf
	v_fmac_f32_dpp v244, v20, v156 row_shr:1 row_mask:0xf bank_mask:0xf
	v_fmac_f32_dpp v245, v21, v157 row_shr:1 row_mask:0xf bank_mask:0xf
	v_fmac_f32_dpp v238, v22, v110 row_shl:1 row_mask:0xf bank_mask:0xf
	v_fmac_f32_dpp v239, v23, v111 row_shl:1 row_mask:0xf bank_mask:0xf
	v_fmac_f32_dpp v240, v24, v112 row_shl:1 row_mask:0xf bank_mask:0xf
	v_fmac_f32_dpp v241, v25, v113 row_shl:1 row_mask:0xf bank_mask:0xf
	v_fmac_f32_dpp v242, v18, v106 row_shl:1 row_mask:0xf bank_mask:0xf
	v_fmac_f32_dpp v243, v19, v107 row_shl:1 row_mask:0xf bank_mask:0xf
	v_fmac_f32_dpp v244, v20, v108 row_shl:1 row_mask:0xf bank_mask:0xf
	v_fmac_f32_dpp v245, v21, v109 row_shl:1 row_mask:0xf bank_mask:0xf
	v_cndmask_b32_e64 v144, 0, v158, s[38:39]
	v_cndmask_b32_e64 v145, 0, v159, s[38:39]
	v_cndmask_b32_e64 v246, 0, v160, s[38:39]
	v_cndmask_b32_e64 v247, 0, v161, s[38:39]
	v_fmac_f32_dpp v238, v30, v144 row_ror:1 row_mask:0xf bank_mask:0xf
	v_fmac_f32_dpp v239, v31, v145 row_ror:1 row_mask:0xf bank_mask:0xf
	v_fmac_f32_dpp v240, v32, v246 row_ror:1 row_mask:0xf bank_mask:0xf
	v_fmac_f32_dpp v241, v33, v247 row_ror:1 row_mask:0xf bank_mask:0xf
	v_cndmask_b32_e64 v144, 0, v154, s[38:39]
	v_cndmask_b32_e64 v145, 0, v155, s[38:39]
	v_cndmask_b32_e64 v246, 0, v156, s[38:39]
	v_cndmask_b32_e64 v247, 0, v157, s[38:39]
	v_fmac_f32_dpp v242, v26, v144 row_ror:1 row_mask:0xf bank_mask:0xf
	v_fmac_f32_dpp v243, v27, v145 row_ror:1 row_mask:0xf bank_mask:0xf
	v_fmac_f32_dpp v244, v28, v246 row_ror:1 row_mask:0xf bank_mask:0xf
	v_fmac_f32_dpp v245, v29, v247 row_ror:1 row_mask:0xf bank_mask:0xf
	v_cndmask_b32_e64 v144, 0, v110, s[40:41]
	v_cndmask_b32_e64 v145, 0, v111, s[40:41]
	v_cndmask_b32_e64 v246, 0, v112, s[40:41]
	v_cndmask_b32_e64 v247, 0, v113, s[40:41]
	v_fmac_f32_dpp v238, v14, v144 row_ror:15 row_mask:0xf bank_mask:0xf
	v_fmac_f32_dpp v239, v15, v145 row_ror:15 row_mask:0xf bank_mask:0xf
	v_fmac_f32_dpp v240, v16, v246 row_ror:15 row_mask:0xf bank_mask:0xf
	v_fmac_f32_dpp v241, v17, v247 row_ror:15 row_mask:0xf bank_mask:0xf
	v_cndmask_b32_e64 v144, 0, v106, s[40:41]
	v_cndmask_b32_e64 v145, 0, v107, s[40:41]
	v_cndmask_b32_e64 v246, 0, v108, s[40:41]
	v_cndmask_b32_e64 v247, 0, v109, s[40:41]
	v_fmac_f32_dpp v242, v10, v144 row_ror:15 row_mask:0xf bank_mask:0xf
	v_fmac_f32_dpp v243, v11, v145 row_ror:15 row_mask:0xf bank_mask:0xf
	v_fmac_f32_dpp v244, v12, v246 row_ror:15 row_mask:0xf bank_mask:0xf
	v_fmac_f32_dpp v245, v13, v247 row_ror:15 row_mask:0xf bank_mask:0xf
	v_pk_mul_f32 v[144:145], v[242:243], s[6:7] op_sel_hi:[1,0]
	v_pk_mul_f32 v[246:247], v[244:245], s[6:7] op_sel_hi:[1,0]
	v_exp_f32_e32 v144, v144
	v_exp_f32_e32 v145, v145
	v_exp_f32_e32 v246, v246
	v_exp_f32_e32 v247, v247
	v_add_f32_e32 v144, 1.0, v144
	v_add_f32_e32 v145, 1.0, v145
	v_add_f32_e32 v246, 1.0, v246
	v_add_f32_e32 v247, 1.0, v247
	v_rcp_f32_e32 v144, v144
	v_rcp_f32_e32 v145, v145
	v_rcp_f32_e32 v246, v246
	v_rcp_f32_e32 v247, v247
	s_nop 0
	v_pk_mul_f32 v[144:145], v[242:243], v[144:145]
	v_pk_mul_f32 v[246:247], v[244:245], v[246:247]
	v_pk_mul_f32 v[144:145], v[238:239], v[144:145]
	v_pk_mul_f32 v[246:247], v[240:241], v[246:247]
	v_cvt_pk_bf16_f32 v130, v144, v145
	v_cvt_pk_bf16_f32 v131, v246, v247
	s_add_u32 s26, s94, 0x18c000
	s_addc_u32 s27, s95, 0
	global_store_dwordx4 v217, v[128:131], s[26:27] sc0 sc1
	v_pk_fma_f32 v[238:239], v[146:147], v[30:31], v[102:103]
	v_pk_fma_f32 v[240:241], v[148:149], v[32:33], v[104:105]
	v_pk_fma_f32 v[242:243], v[114:115], v[26:27], v[98:99]
	v_pk_fma_f32 v[244:245], v[116:117], v[28:29], v[100:101]
	v_fmac_f32_dpp v238, v30, v158 row_shr:1 row_mask:0xf bank_mask:0xf
	v_fmac_f32_dpp v239, v31, v159 row_shr:1 row_mask:0xf bank_mask:0xf
	v_fmac_f32_dpp v240, v32, v160 row_shr:1 row_mask:0xf bank_mask:0xf
	v_fmac_f32_dpp v241, v33, v161 row_shr:1 row_mask:0xf bank_mask:0xf
	v_fmac_f32_dpp v242, v26, v154 row_shr:1 row_mask:0xf bank_mask:0xf
	v_fmac_f32_dpp v243, v27, v155 row_shr:1 row_mask:0xf bank_mask:0xf
	v_fmac_f32_dpp v244, v28, v156 row_shr:1 row_mask:0xf bank_mask:0xf
	v_fmac_f32_dpp v245, v29, v157 row_shr:1 row_mask:0xf bank_mask:0xf
	v_fmac_f32_dpp v238, v30, v110 row_shl:1 row_mask:0xf bank_mask:0xf
	v_fmac_f32_dpp v239, v31, v111 row_shl:1 row_mask:0xf bank_mask:0xf
	v_fmac_f32_dpp v240, v32, v112 row_shl:1 row_mask:0xf bank_mask:0xf
	v_fmac_f32_dpp v241, v33, v113 row_shl:1 row_mask:0xf bank_mask:0xf
	v_fmac_f32_dpp v242, v26, v106 row_shl:1 row_mask:0xf bank_mask:0xf
	v_fmac_f32_dpp v243, v27, v107 row_shl:1 row_mask:0xf bank_mask:0xf
	v_fmac_f32_dpp v244, v28, v108 row_shl:1 row_mask:0xf bank_mask:0xf
	v_fmac_f32_dpp v245, v29, v109 row_shl:1 row_mask:0xf bank_mask:0xf
	s_waitcnt lgkmcnt(0)
	v_cndmask_b32_e64 v144, 0, v158, s[38:39]
	v_cndmask_b32_e64 v145, 0, v159, s[38:39]
	v_cndmask_b32_e64 v246, 0, v160, s[38:39]
	v_cndmask_b32_e64 v247, 0, v161, s[38:39]
	v_pk_fma_f32 v[238:239], v[192:193], v[144:145], v[238:239]
	v_pk_fma_f32 v[240:241], v[194:195], v[246:247], v[240:241]
	v_cndmask_b32_e64 v144, 0, v154, s[38:39]
	v_cndmask_b32_e64 v145, 0, v155, s[38:39]
	v_cndmask_b32_e64 v246, 0, v156, s[38:39]
	v_cndmask_b32_e64 v247, 0, v157, s[38:39]
	v_pk_fma_f32 v[242:243], v[212:213], v[144:145], v[242:243]
	v_pk_fma_f32 v[244:245], v[214:215], v[246:247], v[244:245]
	v_cndmask_b32_e64 v144, 0, v110, s[40:41]
	v_cndmask_b32_e64 v145, 0, v111, s[40:41]
	v_cndmask_b32_e64 v246, 0, v112, s[40:41]
	v_cndmask_b32_e64 v247, 0, v113, s[40:41]
	v_fmac_f32_dpp v238, v22, v144 row_ror:15 row_mask:0xf bank_mask:0xf
	v_fmac_f32_dpp v239, v23, v145 row_ror:15 row_mask:0xf bank_mask:0xf
	v_fmac_f32_dpp v240, v24, v246 row_ror:15 row_mask:0xf bank_mask:0xf
	v_fmac_f32_dpp v241, v25, v247 row_ror:15 row_mask:0xf bank_mask:0xf
	v_cndmask_b32_e64 v144, 0, v106, s[40:41]
	v_cndmask_b32_e64 v145, 0, v107, s[40:41]
	v_cndmask_b32_e64 v246, 0, v108, s[40:41]
	v_cndmask_b32_e64 v247, 0, v109, s[40:41]
	v_fmac_f32_dpp v242, v18, v144 row_ror:15 row_mask:0xf bank_mask:0xf
	v_fmac_f32_dpp v243, v19, v145 row_ror:15 row_mask:0xf bank_mask:0xf
	v_fmac_f32_dpp v244, v20, v246 row_ror:15 row_mask:0xf bank_mask:0xf
	v_fmac_f32_dpp v245, v21, v247 row_ror:15 row_mask:0xf bank_mask:0xf
	v_pk_mul_f32 v[144:145], v[242:243], s[6:7] op_sel_hi:[1,0]
	v_pk_mul_f32 v[246:247], v[244:245], s[6:7] op_sel_hi:[1,0]
	v_exp_f32_e32 v144, v144
	v_exp_f32_e32 v145, v145
	v_exp_f32_e32 v246, v246
	v_exp_f32_e32 v247, v247
	v_add_f32_e32 v144, 1.0, v144
	v_add_f32_e32 v145, 1.0, v145
	v_add_f32_e32 v246, 1.0, v246
	v_add_f32_e32 v247, 1.0, v247
	v_rcp_f32_e32 v144, v144
	v_rcp_f32_e32 v145, v145
	v_rcp_f32_e32 v246, v246
	v_rcp_f32_e32 v247, v247
	s_nop 0
	v_pk_mul_f32 v[144:145], v[242:243], v[144:145]
	v_pk_mul_f32 v[246:247], v[244:245], v[246:247]
	v_pk_mul_f32 v[144:145], v[238:239], v[144:145]
	v_pk_mul_f32 v[246:247], v[240:241], v[246:247]
	v_cvt_pk_bf16_f32 v128, v144, v145
	v_cvt_pk_bf16_f32 v129, v246, v247
	s_add_u32 s26, s94, 0x160000
	s_addc_u32 s27, s95, 0
	global_store_dwordx4 v217, v[126:129], s[26:27] sc0 sc1
	ds_read_b128 v[192:195], v216 offset:16
	ds_read_b128 v[212:215], v216 offset:528
	v_pk_fma_f32 v[238:239], v[146:147], v[38:39], v[102:103]
	v_pk_fma_f32 v[240:241], v[148:149], v[40:41], v[104:105]
	v_pk_fma_f32 v[242:243], v[114:115], v[34:35], v[98:99]
	v_pk_fma_f32 v[244:245], v[116:117], v[36:37], v[100:101]
	v_fmac_f32_dpp v238, v38, v158 row_shr:1 row_mask:0xf bank_mask:0xf
	v_fmac_f32_dpp v239, v39, v159 row_shr:1 row_mask:0xf bank_mask:0xf
	v_fmac_f32_dpp v240, v40, v160 row_shr:1 row_mask:0xf bank_mask:0xf
	v_fmac_f32_dpp v241, v41, v161 row_shr:1 row_mask:0xf bank_mask:0xf
	v_fmac_f32_dpp v242, v34, v154 row_shr:1 row_mask:0xf bank_mask:0xf
	v_fmac_f32_dpp v243, v35, v155 row_shr:1 row_mask:0xf bank_mask:0xf
	v_fmac_f32_dpp v244, v36, v156 row_shr:1 row_mask:0xf bank_mask:0xf
	v_fmac_f32_dpp v245, v37, v157 row_shr:1 row_mask:0xf bank_mask:0xf
	v_fmac_f32_dpp v238, v38, v110 row_shl:1 row_mask:0xf bank_mask:0xf
	v_fmac_f32_dpp v239, v39, v111 row_shl:1 row_mask:0xf bank_mask:0xf
	v_fmac_f32_dpp v240, v40, v112 row_shl:1 row_mask:0xf bank_mask:0xf
	v_fmac_f32_dpp v241, v41, v113 row_shl:1 row_mask:0xf bank_mask:0xf
	v_fmac_f32_dpp v242, v34, v106 row_shl:1 row_mask:0xf bank_mask:0xf
	v_fmac_f32_dpp v243, v35, v107 row_shl:1 row_mask:0xf bank_mask:0xf
	v_fmac_f32_dpp v244, v36, v108 row_shl:1 row_mask:0xf bank_mask:0xf
	v_fmac_f32_dpp v245, v37, v109 row_shl:1 row_mask:0xf bank_mask:0xf
	v_cndmask_b32_e64 v144, 0, v158, s[38:39]
	v_cndmask_b32_e64 v145, 0, v159, s[38:39]
	v_cndmask_b32_e64 v246, 0, v160, s[38:39]
	v_cndmask_b32_e64 v247, 0, v161, s[38:39]
	v_fmac_f32_dpp v238, v46, v144 row_ror:1 row_mask:0xf bank_mask:0xf
	v_fmac_f32_dpp v239, v47, v145 row_ror:1 row_mask:0xf bank_mask:0xf
	v_fmac_f32_dpp v240, v48, v246 row_ror:1 row_mask:0xf bank_mask:0xf
	v_fmac_f32_dpp v241, v49, v247 row_ror:1 row_mask:0xf bank_mask:0xf
	v_cndmask_b32_e64 v144, 0, v154, s[38:39]
	v_cndmask_b32_e64 v145, 0, v155, s[38:39]
	v_cndmask_b32_e64 v246, 0, v156, s[38:39]
	v_cndmask_b32_e64 v247, 0, v157, s[38:39]
	v_fmac_f32_dpp v242, v42, v144 row_ror:1 row_mask:0xf bank_mask:0xf
	v_fmac_f32_dpp v243, v43, v145 row_ror:1 row_mask:0xf bank_mask:0xf
	v_fmac_f32_dpp v244, v44, v246 row_ror:1 row_mask:0xf bank_mask:0xf
	v_fmac_f32_dpp v245, v45, v247 row_ror:1 row_mask:0xf bank_mask:0xf
	s_waitcnt lgkmcnt(0)
	v_cndmask_b32_e64 v144, 0, v110, s[40:41]
	v_cndmask_b32_e64 v145, 0, v111, s[40:41]
	v_cndmask_b32_e64 v246, 0, v112, s[40:41]
	v_cndmask_b32_e64 v247, 0, v113, s[40:41]
	v_pk_fma_f32 v[238:239], v[192:193], v[144:145], v[238:239]
	v_pk_fma_f32 v[240:241], v[194:195], v[246:247], v[240:241]
	v_cndmask_b32_e64 v144, 0, v106, s[40:41]
	v_cndmask_b32_e64 v145, 0, v107, s[40:41]
	v_cndmask_b32_e64 v246, 0, v108, s[40:41]
	v_cndmask_b32_e64 v247, 0, v109, s[40:41]
	v_pk_fma_f32 v[242:243], v[212:213], v[144:145], v[242:243]
	v_pk_fma_f32 v[244:245], v[214:215], v[246:247], v[244:245]
	v_pk_mul_f32 v[144:145], v[242:243], s[6:7] op_sel_hi:[1,0]
	v_pk_mul_f32 v[246:247], v[244:245], s[6:7] op_sel_hi:[1,0]
	v_exp_f32_e32 v144, v144
	v_exp_f32_e32 v145, v145
	v_exp_f32_e32 v246, v246
	v_exp_f32_e32 v247, v247
	v_add_f32_e32 v144, 1.0, v144
	v_add_f32_e32 v145, 1.0, v145
	v_add_f32_e32 v246, 1.0, v246
	v_add_f32_e32 v247, 1.0, v247
	v_rcp_f32_e32 v144, v144
	v_rcp_f32_e32 v145, v145
	v_rcp_f32_e32 v246, v246
	v_rcp_f32_e32 v247, v247
	s_nop 0
	v_pk_mul_f32 v[144:145], v[242:243], v[144:145]
	v_pk_mul_f32 v[246:247], v[244:245], v[246:247]
	v_pk_mul_f32 v[144:145], v[238:239], v[144:145]
	v_pk_mul_f32 v[246:247], v[240:241], v[246:247]
	v_cvt_pk_bf16_f32 v126, v144, v145
	v_cvt_pk_bf16_f32 v127, v246, v247
	s_add_u32 s26, s94, 0x84000
	s_addc_u32 s27, s95, 0
	global_store_dwordx4 v217, v[124:127], s[26:27] sc0 sc1
	v_pk_fma_f32 v[238:239], v[146:147], v[46:47], v[102:103]
	v_pk_fma_f32 v[240:241], v[148:149], v[48:49], v[104:105]
	v_pk_fma_f32 v[242:243], v[114:115], v[42:43], v[98:99]
	v_pk_fma_f32 v[244:245], v[116:117], v[44:45], v[100:101]
	v_fmac_f32_dpp v238, v46, v158 row_shr:1 row_mask:0xf bank_mask:0xf
	v_fmac_f32_dpp v239, v47, v159 row_shr:1 row_mask:0xf bank_mask:0xf
	v_fmac_f32_dpp v240, v48, v160 row_shr:1 row_mask:0xf bank_mask:0xf
	v_fmac_f32_dpp v241, v49, v161 row_shr:1 row_mask:0xf bank_mask:0xf
	v_fmac_f32_dpp v242, v42, v154 row_shr:1 row_mask:0xf bank_mask:0xf
	v_fmac_f32_dpp v243, v43, v155 row_shr:1 row_mask:0xf bank_mask:0xf
	v_fmac_f32_dpp v244, v44, v156 row_shr:1 row_mask:0xf bank_mask:0xf
	v_fmac_f32_dpp v245, v45, v157 row_shr:1 row_mask:0xf bank_mask:0xf
	v_fmac_f32_dpp v238, v46, v110 row_shl:1 row_mask:0xf bank_mask:0xf
	v_fmac_f32_dpp v239, v47, v111 row_shl:1 row_mask:0xf bank_mask:0xf
	v_fmac_f32_dpp v240, v48, v112 row_shl:1 row_mask:0xf bank_mask:0xf
	v_fmac_f32_dpp v241, v49, v113 row_shl:1 row_mask:0xf bank_mask:0xf
	v_fmac_f32_dpp v242, v42, v106 row_shl:1 row_mask:0xf bank_mask:0xf
	v_fmac_f32_dpp v243, v43, v107 row_shl:1 row_mask:0xf bank_mask:0xf
	v_fmac_f32_dpp v244, v44, v108 row_shl:1 row_mask:0xf bank_mask:0xf
	v_fmac_f32_dpp v245, v45, v109 row_shl:1 row_mask:0xf bank_mask:0xf
	v_cndmask_b32_e64 v144, 0, v158, s[38:39]
	v_cndmask_b32_e64 v145, 0, v159, s[38:39]
	v_cndmask_b32_e64 v246, 0, v160, s[38:39]
	v_cndmask_b32_e64 v247, 0, v161, s[38:39]
	v_fmac_f32_dpp v238, v54, v144 row_ror:1 row_mask:0xf bank_mask:0xf
	v_fmac_f32_dpp v239, v55, v145 row_ror:1 row_mask:0xf bank_mask:0xf
	v_fmac_f32_dpp v240, v56, v246 row_ror:1 row_mask:0xf bank_mask:0xf
	v_fmac_f32_dpp v241, v57, v247 row_ror:1 row_mask:0xf bank_mask:0xf
	v_cndmask_b32_e64 v144, 0, v154, s[38:39]
	v_cndmask_b32_e64 v145, 0, v155, s[38:39]
	v_cndmask_b32_e64 v246, 0, v156, s[38:39]
	v_cndmask_b32_e64 v247, 0, v157, s[38:39]
	v_fmac_f32_dpp v242, v50, v144 row_ror:1 row_mask:0xf bank_mask:0xf
	v_fmac_f32_dpp v243, v51, v145 row_ror:1 row_mask:0xf bank_mask:0xf
	v_fmac_f32_dpp v244, v52, v246 row_ror:1 row_mask:0xf bank_mask:0xf
	v_fmac_f32_dpp v245, v53, v247 row_ror:1 row_mask:0xf bank_mask:0xf
	v_cndmask_b32_e64 v144, 0, v110, s[40:41]
	v_cndmask_b32_e64 v145, 0, v111, s[40:41]
	v_cndmask_b32_e64 v246, 0, v112, s[40:41]
	v_cndmask_b32_e64 v247, 0, v113, s[40:41]
	v_fmac_f32_dpp v238, v38, v144 row_ror:15 row_mask:0xf bank_mask:0xf
	v_fmac_f32_dpp v239, v39, v145 row_ror:15 row_mask:0xf bank_mask:0xf
	v_fmac_f32_dpp v240, v40, v246 row_ror:15 row_mask:0xf bank_mask:0xf
	v_fmac_f32_dpp v241, v41, v247 row_ror:15 row_mask:0xf bank_mask:0xf
	v_cndmask_b32_e64 v144, 0, v106, s[40:41]
	v_cndmask_b32_e64 v145, 0, v107, s[40:41]
	v_cndmask_b32_e64 v246, 0, v108, s[40:41]
	v_cndmask_b32_e64 v247, 0, v109, s[40:41]
	v_fmac_f32_dpp v242, v34, v144 row_ror:15 row_mask:0xf bank_mask:0xf
	v_fmac_f32_dpp v243, v35, v145 row_ror:15 row_mask:0xf bank_mask:0xf
	v_fmac_f32_dpp v244, v36, v246 row_ror:15 row_mask:0xf bank_mask:0xf
	v_fmac_f32_dpp v245, v37, v247 row_ror:15 row_mask:0xf bank_mask:0xf
	v_pk_mul_f32 v[144:145], v[242:243], s[6:7] op_sel_hi:[1,0]
	v_pk_mul_f32 v[246:247], v[244:245], s[6:7] op_sel_hi:[1,0]
	v_exp_f32_e32 v144, v144
	v_exp_f32_e32 v145, v145
	v_exp_f32_e32 v246, v246
	v_exp_f32_e32 v247, v247
	v_add_f32_e32 v144, 1.0, v144
	v_add_f32_e32 v145, 1.0, v145
	v_add_f32_e32 v246, 1.0, v246
	v_add_f32_e32 v247, 1.0, v247
	v_rcp_f32_e32 v144, v144
	v_rcp_f32_e32 v145, v145
	v_rcp_f32_e32 v246, v246
	v_rcp_f32_e32 v247, v247
	s_nop 0
	v_pk_mul_f32 v[144:145], v[242:243], v[144:145]
	v_pk_mul_f32 v[246:247], v[244:245], v[246:247]
	v_pk_mul_f32 v[144:145], v[238:239], v[144:145]
	v_pk_mul_f32 v[246:247], v[240:241], v[246:247]
	v_cvt_pk_bf16_f32 v124, v144, v145
	v_cvt_pk_bf16_f32 v125, v246, v247
	s_add_u32 s26, s94, 0x58000
	s_addc_u32 s27, s95, 0
	global_store_dwordx4 v217, v[122:125], s[26:27] sc0 sc1
	v_pk_fma_f32 v[238:239], v[146:147], v[54:55], v[102:103]
	v_pk_fma_f32 v[240:241], v[148:149], v[56:57], v[104:105]
	v_pk_fma_f32 v[242:243], v[114:115], v[50:51], v[98:99]
	v_pk_fma_f32 v[244:245], v[116:117], v[52:53], v[100:101]
	v_fmac_f32_dpp v238, v54, v158 row_shr:1 row_mask:0xf bank_mask:0xf
	v_fmac_f32_dpp v239, v55, v159 row_shr:1 row_mask:0xf bank_mask:0xf
	v_fmac_f32_dpp v240, v56, v160 row_shr:1 row_mask:0xf bank_mask:0xf
	v_fmac_f32_dpp v241, v57, v161 row_shr:1 row_mask:0xf bank_mask:0xf
	v_fmac_f32_dpp v242, v50, v154 row_shr:1 row_mask:0xf bank_mask:0xf
	v_fmac_f32_dpp v243, v51, v155 row_shr:1 row_mask:0xf bank_mask:0xf
	v_fmac_f32_dpp v244, v52, v156 row_shr:1 row_mask:0xf bank_mask:0xf
	v_fmac_f32_dpp v245, v53, v157 row_shr:1 row_mask:0xf bank_mask:0xf
	v_fmac_f32_dpp v238, v54, v110 row_shl:1 row_mask:0xf bank_mask:0xf
	v_fmac_f32_dpp v239, v55, v111 row_shl:1 row_mask:0xf bank_mask:0xf
	v_fmac_f32_dpp v240, v56, v112 row_shl:1 row_mask:0xf bank_mask:0xf
	v_fmac_f32_dpp v241, v57, v113 row_shl:1 row_mask:0xf bank_mask:0xf
	v_fmac_f32_dpp v242, v50, v106 row_shl:1 row_mask:0xf bank_mask:0xf
	v_fmac_f32_dpp v243, v51, v107 row_shl:1 row_mask:0xf bank_mask:0xf
	v_fmac_f32_dpp v244, v52, v108 row_shl:1 row_mask:0xf bank_mask:0xf
	v_fmac_f32_dpp v245, v53, v109 row_shl:1 row_mask:0xf bank_mask:0xf
	v_cndmask_b32_e64 v144, 0, v158, s[38:39]
	v_cndmask_b32_e64 v145, 0, v159, s[38:39]
	v_cndmask_b32_e64 v246, 0, v160, s[38:39]
	v_cndmask_b32_e64 v247, 0, v161, s[38:39]
	v_fmac_f32_dpp v238, v62, v144 row_ror:1 row_mask:0xf bank_mask:0xf
	v_fmac_f32_dpp v239, v63, v145 row_ror:1 row_mask:0xf bank_mask:0xf
	v_fmac_f32_dpp v240, v64, v246 row_ror:1 row_mask:0xf bank_mask:0xf
	v_fmac_f32_dpp v241, v65, v247 row_ror:1 row_mask:0xf bank_mask:0xf
	v_cndmask_b32_e64 v144, 0, v154, s[38:39]
	v_cndmask_b32_e64 v145, 0, v155, s[38:39]
	v_cndmask_b32_e64 v246, 0, v156, s[38:39]
	v_cndmask_b32_e64 v247, 0, v157, s[38:39]
	v_fmac_f32_dpp v242, v58, v144 row_ror:1 row_mask:0xf bank_mask:0xf
	v_fmac_f32_dpp v243, v59, v145 row_ror:1 row_mask:0xf bank_mask:0xf
	v_fmac_f32_dpp v244, v60, v246 row_ror:1 row_mask:0xf bank_mask:0xf
	v_fmac_f32_dpp v245, v61, v247 row_ror:1 row_mask:0xf bank_mask:0xf
	v_cndmask_b32_e64 v144, 0, v110, s[40:41]
	v_cndmask_b32_e64 v145, 0, v111, s[40:41]
	v_cndmask_b32_e64 v246, 0, v112, s[40:41]
	v_cndmask_b32_e64 v247, 0, v113, s[40:41]
	v_fmac_f32_dpp v238, v46, v144 row_ror:15 row_mask:0xf bank_mask:0xf
	v_fmac_f32_dpp v239, v47, v145 row_ror:15 row_mask:0xf bank_mask:0xf
	v_fmac_f32_dpp v240, v48, v246 row_ror:15 row_mask:0xf bank_mask:0xf
	v_fmac_f32_dpp v241, v49, v247 row_ror:15 row_mask:0xf bank_mask:0xf
	v_cndmask_b32_e64 v144, 0, v106, s[40:41]
	v_cndmask_b32_e64 v145, 0, v107, s[40:41]
	v_cndmask_b32_e64 v246, 0, v108, s[40:41]
	v_cndmask_b32_e64 v247, 0, v109, s[40:41]
	v_fmac_f32_dpp v242, v42, v144 row_ror:15 row_mask:0xf bank_mask:0xf
	v_fmac_f32_dpp v243, v43, v145 row_ror:15 row_mask:0xf bank_mask:0xf
	v_fmac_f32_dpp v244, v44, v246 row_ror:15 row_mask:0xf bank_mask:0xf
	v_fmac_f32_dpp v245, v45, v247 row_ror:15 row_mask:0xf bank_mask:0xf
	v_pk_mul_f32 v[144:145], v[242:243], s[6:7] op_sel_hi:[1,0]
	v_pk_mul_f32 v[246:247], v[244:245], s[6:7] op_sel_hi:[1,0]
	v_exp_f32_e32 v144, v144
	v_exp_f32_e32 v145, v145
	v_exp_f32_e32 v246, v246
	v_exp_f32_e32 v247, v247
	v_add_f32_e32 v144, 1.0, v144
	v_add_f32_e32 v145, 1.0, v145
	v_add_f32_e32 v246, 1.0, v246
	v_add_f32_e32 v247, 1.0, v247
	v_rcp_f32_e32 v144, v144
	v_rcp_f32_e32 v145, v145
	v_rcp_f32_e32 v246, v246
	v_rcp_f32_e32 v247, v247
	s_nop 0
	v_pk_mul_f32 v[144:145], v[242:243], v[144:145]
	v_pk_mul_f32 v[246:247], v[244:245], v[246:247]
	v_pk_mul_f32 v[144:145], v[238:239], v[144:145]
	v_pk_mul_f32 v[246:247], v[240:241], v[246:247]
	v_cvt_pk_bf16_f32 v122, v144, v145
	v_cvt_pk_bf16_f32 v123, v246, v247
	s_add_u32 s26, s94, 0x2c000
	s_addc_u32 s27, s95, 0
	global_store_dwordx4 v217, v[120:123], s[26:27] sc0 sc1
	v_pk_fma_f32 v[238:239], v[146:147], v[62:63], v[102:103]
	v_pk_fma_f32 v[240:241], v[148:149], v[64:65], v[104:105]
	v_pk_fma_f32 v[242:243], v[114:115], v[58:59], v[98:99]
	v_pk_fma_f32 v[244:245], v[116:117], v[60:61], v[100:101]
	v_fmac_f32_dpp v238, v62, v158 row_shr:1 row_mask:0xf bank_mask:0xf
	v_fmac_f32_dpp v239, v63, v159 row_shr:1 row_mask:0xf bank_mask:0xf
	v_fmac_f32_dpp v240, v64, v160 row_shr:1 row_mask:0xf bank_mask:0xf
	v_fmac_f32_dpp v241, v65, v161 row_shr:1 row_mask:0xf bank_mask:0xf
	v_fmac_f32_dpp v242, v58, v154 row_shr:1 row_mask:0xf bank_mask:0xf
	v_fmac_f32_dpp v243, v59, v155 row_shr:1 row_mask:0xf bank_mask:0xf
	v_fmac_f32_dpp v244, v60, v156 row_shr:1 row_mask:0xf bank_mask:0xf
	v_fmac_f32_dpp v245, v61, v157 row_shr:1 row_mask:0xf bank_mask:0xf
	v_fmac_f32_dpp v238, v62, v110 row_shl:1 row_mask:0xf bank_mask:0xf
	v_fmac_f32_dpp v239, v63, v111 row_shl:1 row_mask:0xf bank_mask:0xf
	v_fmac_f32_dpp v240, v64, v112 row_shl:1 row_mask:0xf bank_mask:0xf
	v_fmac_f32_dpp v241, v65, v113 row_shl:1 row_mask:0xf bank_mask:0xf
	v_fmac_f32_dpp v242, v58, v106 row_shl:1 row_mask:0xf bank_mask:0xf
	v_fmac_f32_dpp v243, v59, v107 row_shl:1 row_mask:0xf bank_mask:0xf
	v_fmac_f32_dpp v244, v60, v108 row_shl:1 row_mask:0xf bank_mask:0xf
	v_fmac_f32_dpp v245, v61, v109 row_shl:1 row_mask:0xf bank_mask:0xf
	s_waitcnt lgkmcnt(0)
	s_cmp_eq_u32 s4, 0
	s_cbranch_scc1 .Lupc_7
	v_cndmask_b32_e64 v144, 0, v158, s[38:39]
	v_cndmask_b32_e64 v145, 0, v159, s[38:39]
	v_cndmask_b32_e64 v246, 0, v160, s[38:39]
	v_cndmask_b32_e64 v247, 0, v161, s[38:39]
	v_pk_fma_f32 v[238:239], v[192:193], v[144:145], v[238:239]
	v_pk_fma_f32 v[240:241], v[194:195], v[246:247], v[240:241]
	v_cndmask_b32_e64 v144, 0, v154, s[38:39]
	v_cndmask_b32_e64 v145, 0, v155, s[38:39]
	v_cndmask_b32_e64 v246, 0, v156, s[38:39]
	v_cndmask_b32_e64 v247, 0, v157, s[38:39]
	v_pk_fma_f32 v[242:243], v[212:213], v[144:145], v[242:243]
	v_pk_fma_f32 v[244:245], v[214:215], v[246:247], v[244:245]

.Lupc_8:
	v_pk_mul_f32 v[144:145], v[242:243], s[6:7] op_sel_hi:[1,0]
	v_pk_mul_f32 v[246:247], v[244:245], s[6:7] op_sel_hi:[1,0]
	v_exp_f32_e32 v144, v144
	v_exp_f32_e32 v145, v145
	v_exp_f32_e32 v246, v246
	v_exp_f32_e32 v247, v247
	v_add_f32_e32 v144, 1.0, v144
	v_add_f32_e32 v145, 1.0, v145
	v_add_f32_e32 v246, 1.0, v246
	v_add_f32_e32 v247, 1.0, v247
	v_rcp_f32_e32 v144, v144
	v_rcp_f32_e32 v145, v145
	v_rcp_f32_e32 v246, v246
	v_rcp_f32_e32 v247, v247
	s_nop 0
	v_pk_mul_f32 v[144:145], v[242:243], v[144:145]
	v_pk_mul_f32 v[246:247], v[244:245], v[246:247]
	v_pk_mul_f32 v[144:145], v[238:239], v[144:145]
	v_pk_mul_f32 v[246:247], v[240:241], v[246:247]
	v_cvt_pk_bf16_f32 v120, v144, v145
	v_cvt_pk_bf16_f32 v121, v246, v247
	global_store_dwordx4 v217, v[118:121], s[94:95] sc0 sc1
	s_andn2_b64 vcc, exec, s[20:21]
	s_mov_b64 s[4:5], -1
	s_cbranch_vccnz .LBB0_179
	v_readlane_b32 s4, v255, 3
	v_readlane_b32 s5, v255, 4
	s_and_b64 vcc, exec, s[4:5]
	s_cbranch_vccnz .LBB0_178
	s_barrier
	s_branch .LBB0_178

.LBB0_374:
	s_lshl_b32 s4, s9, 8
	s_add_i32 s4, s4, s12
	v_readlane_b32 s5, v253, 34
	s_lshl_b32 s40, s8, 8
	v_readlane_b32 s6, v255, 15
	v_readlane_b32 s7, v254, 55
	s_or_b32 s40, s40, s5
	s_sub_i32 s41, s9, 32
	s_lshr_b32 s41, s41, 3
	s_add_i32 s41, s41, 1
	s_mul_i32 s41, s41, 0xc000
	s_cmp_lt_i32 s9, 32
	s_cselect_b32 s41, 0, s41
	s_add_u32 s6, s6, s41
	s_addc_u32 s7, s7, 0
	s_lshl_b32 s41, s40, 2
	s_add_u32 s6, s6, s41
	s_addc_u32 s7, s7, 0
	v_lshlrev_b32_e32 v251, 5, v237
	s_and_b64 vcc, exec, s[34:35]
	s_cbranch_vccz .Lres_xpath
	s_lshl_b32 s5, s4, 3
	s_add_u32 s74, s68, s5
	s_addc_u32 s75, s69, 0
	v_lshlrev_b32_e32 v196, 3, v238
	global_load_dwordx2 v[172:173], v196, s[74:75] offset:0
	global_load_dwordx2 v[174:175], v196, s[74:75] offset:128
	global_load_dwordx2 v[176:177], v196, s[74:75] offset:256
	global_load_dwordx2 v[178:179], v196, s[74:75] offset:384
	global_load_dwordx2 v[180:181], v196, s[74:75] offset:1024
	global_load_dwordx2 v[182:183], v196, s[74:75] offset:1152
	global_load_dwordx2 v[184:185], v196, s[74:75] offset:1280
	global_load_dwordx2 v[186:187], v196, s[74:75] offset:1408
	global_load_dwordx4 v[188:191], v251, s[6:7] offset:0
	global_load_dwordx4 v[192:195], v251, s[6:7] offset:16
	s_add_u32 s74, s62, s41
	s_addc_u32 s75, s63, 0
	global_load_dwordx4 v[208:211], v251, s[74:75] offset:0
	global_load_dwordx4 v[212:215], v251, s[74:75] offset:16
	s_add_u32 s74, s60, s41
	s_addc_u32 s75, s61, 0
	global_load_dwordx4 v[142:145], v251, s[74:75] offset:0
	global_load_dwordx4 v[146:149], v251, s[74:75] offset:16
	s_lshl_b32 s5, s4, 12
	s_add_u32 s14, s0, s5
	s_addc_u32 s15, s1, 0
	s_lshl_b32 s5, s40, 1
	s_add_u32 s14, s14, s5
	s_addc_u32 s15, s15, 0
	v_lshlrev_b32_e32 v250, 12, v238
	v_lshl_or_b32 v250, v237, 4, v250
	global_load_dwordx4 v[122:125], v250, s[14:15] offset:0
	s_add_u32 s74, s14, 0x10000
	s_addc_u32 s75, s15, 0
	global_load_dwordx4 v[126:129], v250, s[74:75] offset:0
	s_add_u32 s74, s14, 0x20000
	s_addc_u32 s75, s15, 0
	global_load_dwordx4 v[134:137], v250, s[74:75] offset:0
	s_add_u32 s74, s14, 0x30000
	s_addc_u32 s75, s15, 0
	global_load_dwordx4 v[158:161], v250, s[74:75] offset:0
	s_add_u32 s74, s14, 0x80000
	s_addc_u32 s75, s15, 0
	global_load_dwordx4 v[242:245], v250, s[74:75] offset:0
	s_add_u32 s74, s14, 0x90000
	s_addc_u32 s75, s15, 0
	global_load_dwordx4 v[246:249], v250, s[74:75] offset:0
	s_mov_b32 s16, 0x3fb504f3
	s_waitcnt vmcnt(12)
	v_mul_f32_e64 v172, -v172, v173
	v_mul_f32_e64 v174, -v174, v175
	v_mul_f32_e64 v176, -v176, v177
	v_mul_f32_e64 v178, -v178, v179
	v_mul_f32_e64 v180, -v180, v181
	v_mul_f32_e64 v182, -v182, v183
	v_mul_f32_e64 v184, -v184, v185
	v_mul_f32_e64 v186, -v186, v187
	s_waitcnt vmcnt(6)
	v_mul_f32_e32 v208, s16, v208
	v_mul_f32_e32 v142, s16, v142
	v_mul_f32_e32 v209, s16, v209
	v_mul_f32_e32 v143, s16, v143
	v_mul_f32_e32 v210, s16, v210
	v_mul_f32_e32 v144, s16, v144
	v_mul_f32_e32 v211, s16, v211
	v_mul_f32_e32 v145, s16, v145
	v_mul_f32_e32 v212, s16, v212
	v_mul_f32_e32 v146, s16, v146
	v_mul_f32_e32 v213, s16, v213
	v_mul_f32_e32 v147, s16, v147
	v_mul_f32_e32 v214, s16, v214
	v_mul_f32_e32 v148, s16, v148
	v_mul_f32_e32 v215, s16, v215
	v_mul_f32_e32 v149, s16, v149
	s_waitcnt vmcnt(5)
	v_lshlrev_b32_e32 v150, 16, v122
	v_and_b32_e32 v151, 0xffff0000, v122
	v_lshlrev_b32_e32 v152, 16, v123
	v_and_b32_e32 v153, 0xffff0000, v123
	v_lshlrev_b32_e32 v154, 16, v124
	v_and_b32_e32 v155, 0xffff0000, v124
	v_lshlrev_b32_e32 v156, 16, v125
	v_and_b32_e32 v157, 0xffff0000, v125
	v_fma_f32 v150, v150, v173, v172
	v_fma_f32 v151, v151, v173, v172
	v_fma_f32 v152, v152, v173, v172
	v_fma_f32 v153, v153, v173, v172
	v_fma_f32 v154, v154, v173, v172
	v_fma_f32 v155, v155, v173, v172
	v_fma_f32 v156, v156, v173, v172
	v_fma_f32 v157, v157, v173, v172
	v_fma_f32 v150, v150, v208, v142
	v_fma_f32 v151, v151, v209, v143
	v_fma_f32 v152, v152, v210, v144
	v_fma_f32 v153, v153, v211, v145
	v_fma_f32 v154, v154, v212, v146
	v_fma_f32 v155, v155, v213, v147
	v_fma_f32 v156, v156, v214, v148
	v_fma_f32 v157, v157, v215, v149
	v_fmac_f32_e32 v150, v138, v188
	v_fmac_f32_e32 v151, v139, v189
	v_fmac_f32_e32 v152, v140, v190
	v_fmac_f32_e32 v153, v141, v191
	v_fmac_f32_e32 v154, v130, v192
	v_fmac_f32_e32 v155, v131, v193
	v_fmac_f32_e32 v156, v132, v194
	v_fmac_f32_e32 v157, v133, v195
	v_cvt_pk_bf16_f32 v150, v150, v151
	v_cvt_pk_bf16_f32 v151, v152, v153
	v_cvt_pk_bf16_f32 v152, v154, v155
	v_cvt_pk_bf16_f32 v153, v156, v157
	global_store_dwordx4 v250, v[150:153], s[14:15] offset:0 sc0 sc1
	s_add_u32 s74, s14, 0xa0000
	s_addc_u32 s75, s15, 0
	global_load_dwordx4 v[122:125], v250, s[74:75] offset:0
	s_nop 1
	s_waitcnt vmcnt(6)
	v_lshlrev_b32_e32 v150, 16, v126
	v_and_b32_e32 v151, 0xffff0000, v126
	v_lshlrev_b32_e32 v152, 16, v127
	v_and_b32_e32 v153, 0xffff0000, v127
	v_lshlrev_b32_e32 v154, 16, v128
	v_and_b32_e32 v155, 0xffff0000, v128
	v_lshlrev_b32_e32 v156, 16, v129
	v_and_b32_e32 v157, 0xffff0000, v129
	v_fma_f32 v150, v150, v175, v174
	v_fma_f32 v151, v151, v175, v174
	v_fma_f32 v152, v152, v175, v174
	v_fma_f32 v153, v153, v175, v174
	v_fma_f32 v154, v154, v175, v174
	v_fma_f32 v155, v155, v175, v174
	v_fma_f32 v156, v156, v175, v174
	v_fma_f32 v157, v157, v175, v174
	v_fma_f32 v150, v150, v208, v142
	v_fma_f32 v151, v151, v209, v143
	v_fma_f32 v152, v152, v210, v144
	v_fma_f32 v153, v153, v211, v145
	v_fma_f32 v154, v154, v212, v146
	v_fma_f32 v155, v155, v213, v147
	v_fma_f32 v156, v156, v214, v148
	v_fma_f32 v157, v157, v215, v149
	v_fmac_f32_e32 v150, v118, v188
	v_fmac_f32_e32 v151, v119, v189
	v_fmac_f32_e32 v152, v120, v190
	v_fmac_f32_e32 v153, v121, v191
	v_fmac_f32_e32 v154, v114, v192
	v_fmac_f32_e32 v155, v115, v193
	v_fmac_f32_e32 v156, v116, v194
	v_fmac_f32_e32 v157, v117, v195
	v_cvt_pk_bf16_f32 v150, v150, v151
	v_cvt_pk_bf16_f32 v151, v152, v153
	v_cvt_pk_bf16_f32 v152, v154, v155
	v_cvt_pk_bf16_f32 v153, v156, v157
	s_add_u32 s38, s14, 0x10000
	s_addc_u32 s39, s15, 0
	global_store_dwordx4 v250, v[150:153], s[38:39] offset:0 sc0 sc1
	s_add_u32 s74, s14, 0xb0000
	s_addc_u32 s75, s15, 0
	global_load_dwordx4 v[126:129], v250, s[74:75] offset:0
	s_nop 1
	s_waitcnt vmcnt(7)
	v_lshlrev_b32_e32 v150, 16, v134
	v_and_b32_e32 v151, 0xffff0000, v134
	v_lshlrev_b32_e32 v152, 16, v135
	v_and_b32_e32 v153, 0xffff0000, v135
	v_lshlrev_b32_e32 v154, 16, v136
	v_and_b32_e32 v155, 0xffff0000, v136
	v_lshlrev_b32_e32 v156, 16, v137
	v_and_b32_e32 v157, 0xffff0000, v137
	v_fma_f32 v150, v150, v177, v176
	v_fma_f32 v151, v151, v177, v176
	v_fma_f32 v152, v152, v177, v176
	v_fma_f32 v153, v153, v177, v176
	v_fma_f32 v154, v154, v177, v176
	v_fma_f32 v155, v155, v177, v176
	v_fma_f32 v156, v156, v177, v176
	v_fma_f32 v157, v157, v177, v176
	v_fma_f32 v150, v150, v208, v142
	v_fma_f32 v151, v151, v209, v143
	v_fma_f32 v152, v152, v210, v144
	v_fma_f32 v153, v153, v211, v145
	v_fma_f32 v154, v154, v212, v146
	v_fma_f32 v155, v155, v213, v147
	v_fma_f32 v156, v156, v214, v148
	v_fma_f32 v157, v157, v215, v149
	v_fmac_f32_e32 v150, v110, v188
	v_fmac_f32_e32 v151, v111, v189
	v_fmac_f32_e32 v152, v112, v190
	v_fmac_f32_e32 v153, v113, v191
	v_fmac_f32_e32 v154, v106, v192
	v_fmac_f32_e32 v155, v107, v193
	v_fmac_f32_e32 v156, v108, v194
	v_fmac_f32_e32 v157, v109, v195
	v_cvt_pk_bf16_f32 v150, v150, v151
	v_cvt_pk_bf16_f32 v151, v152, v153
	v_cvt_pk_bf16_f32 v152, v154, v155
	v_cvt_pk_bf16_f32 v153, v156, v157
	s_add_u32 s38, s14, 0x20000
	s_addc_u32 s39, s15, 0
	global_store_dwordx4 v250, v[150:153], s[38:39] offset:0 sc0 sc1
	global_load_dwordx4 v[138:141], v251, s[6:7] offset:512
	global_load_dwordx4 v[130:133], v251, s[6:7] offset:528
	s_add_u32 s74, s62, s41
	s_addc_u32 s75, s63, 0
	global_load_dwordx4 v[118:121], v251, s[74:75] offset:512
	global_load_dwordx4 v[114:117], v251, s[74:75] offset:528
	s_add_u32 s74, s60, s41
	s_addc_u32 s75, s61, 0
	global_load_dwordx4 v[110:113], v251, s[74:75] offset:512
	global_load_dwordx4 v[106:109], v251, s[74:75] offset:528
	global_load_dwordx4 v[134:137], v250, s[14:15] offset:256
	s_nop 1
	s_waitcnt vmcnt(14)
	v_lshlrev_b32_e32 v150, 16, v158
	v_and_b32_e32 v151, 0xffff0000, v158
	v_lshlrev_b32_e32 v152, 16, v159
	v_and_b32_e32 v153, 0xffff0000, v159
	v_lshlrev_b32_e32 v154, 16, v160
	v_and_b32_e32 v155, 0xffff0000, v160
	v_lshlrev_b32_e32 v156, 16, v161
	v_and_b32_e32 v157, 0xffff0000, v161
	v_fma_f32 v150, v150, v179, v178
	v_fma_f32 v151, v151, v179, v178
	v_fma_f32 v152, v152, v179, v178
	v_fma_f32 v153, v153, v179, v178
	v_fma_f32 v154, v154, v179, v178
	v_fma_f32 v155, v155, v179, v178
	v_fma_f32 v156, v156, v179, v178
	v_fma_f32 v157, v157, v179, v178
	v_fma_f32 v150, v150, v208, v142
	v_fma_f32 v151, v151, v209, v143
	v_fma_f32 v152, v152, v210, v144
	v_fma_f32 v153, v153, v211, v145
	v_fma_f32 v154, v154, v212, v146
	v_fma_f32 v155, v155, v213, v147
	v_fma_f32 v156, v156, v214, v148
	v_fma_f32 v157, v157, v215, v149
	v_fmac_f32_e32 v150, v102, v188
	v_fmac_f32_e32 v151, v103, v189
	v_fmac_f32_e32 v152, v104, v190
	v_fmac_f32_e32 v153, v105, v191
	v_fmac_f32_e32 v154, v98, v192
	v_fmac_f32_e32 v155, v99, v193
	v_fmac_f32_e32 v156, v100, v194
	v_fmac_f32_e32 v157, v101, v195
	v_cvt_pk_bf16_f32 v150, v150, v151
	v_cvt_pk_bf16_f32 v151, v152, v153
	v_cvt_pk_bf16_f32 v152, v154, v155
	v_cvt_pk_bf16_f32 v153, v156, v157
	s_add_u32 s38, s14, 0x30000
	s_addc_u32 s39, s15, 0
	global_store_dwordx4 v250, v[150:153], s[38:39] offset:0 sc0 sc1
	s_add_u32 s74, s14, 0x10000
	s_addc_u32 s75, s15, 0
	global_load_dwordx4 v[158:161], v250, s[74:75] offset:256
	s_nop 1
	s_waitcnt vmcnt(15)
	v_lshlrev_b32_e32 v150, 16, v242
	v_and_b32_e32 v151, 0xffff0000, v242
	v_lshlrev_b32_e32 v152, 16, v243
	v_and_b32_e32 v153, 0xffff0000, v243
	v_lshlrev_b32_e32 v154, 16, v244
	v_and_b32_e32 v155, 0xffff0000, v244
	v_lshlrev_b32_e32 v156, 16, v245
	v_and_b32_e32 v157, 0xffff0000, v245
	v_fma_f32 v150, v150, v181, v180
	v_fma_f32 v151, v151, v181, v180
	v_fma_f32 v152, v152, v181, v180
	v_fma_f32 v153, v153, v181, v180
	v_fma_f32 v154, v154, v181, v180
	v_fma_f32 v155, v155, v181, v180
	v_fma_f32 v156, v156, v181, v180
	v_fma_f32 v157, v157, v181, v180
	v_fma_f32 v150, v150, v208, v142
	v_fma_f32 v151, v151, v209, v143
	v_fma_f32 v152, v152, v210, v144
	v_fma_f32 v153, v153, v211, v145
	v_fma_f32 v154, v154, v212, v146
	v_fma_f32 v155, v155, v213, v147
	v_fma_f32 v156, v156, v214, v148
	v_fma_f32 v157, v157, v215, v149
	v_fmac_f32_e32 v150, v94, v188
	v_fmac_f32_e32 v151, v95, v189
	v_fmac_f32_e32 v152, v96, v190
	v_fmac_f32_e32 v153, v97, v191
	v_fmac_f32_e32 v154, v90, v192
	v_fmac_f32_e32 v155, v91, v193
	v_fmac_f32_e32 v156, v92, v194
	v_fmac_f32_e32 v157, v93, v195
	v_cvt_pk_bf16_f32 v150, v150, v151
	v_cvt_pk_bf16_f32 v151, v152, v153
	v_cvt_pk_bf16_f32 v152, v154, v155
	v_cvt_pk_bf16_f32 v153, v156, v157
	s_add_u32 s38, s14, 0x80000
	s_addc_u32 s39, s15, 0
	global_store_dwordx4 v250, v[150:153], s[38:39] offset:0 sc0 sc1
	s_add_u32 s74, s14, 0x20000
	s_addc_u32 s75, s15, 0
	global_load_dwordx4 v[242:245], v250, s[74:75] offset:256
	s_nop 1
	s_waitcnt vmcnt(16)
	v_lshlrev_b32_e32 v150, 16, v246
	v_and_b32_e32 v151, 0xffff0000, v246
	v_lshlrev_b32_e32 v152, 16, v247
	v_and_b32_e32 v153, 0xffff0000, v247
	v_lshlrev_b32_e32 v154, 16, v248
	v_and_b32_e32 v155, 0xffff0000, v248
	v_lshlrev_b32_e32 v156, 16, v249
	v_and_b32_e32 v157, 0xffff0000, v249
	v_fma_f32 v150, v150, v183, v182
	v_fma_f32 v151, v151, v183, v182
	v_fma_f32 v152, v152, v183, v182
	v_fma_f32 v153, v153, v183, v182
	v_fma_f32 v154, v154, v183, v182
	v_fma_f32 v155, v155, v183, v182
	v_fma_f32 v156, v156, v183, v182
	v_fma_f32 v157, v157, v183, v182
	v_fma_f32 v150, v150, v208, v142
	v_fma_f32 v151, v151, v209, v143
	v_fma_f32 v152, v152, v210, v144
	v_fma_f32 v153, v153, v211, v145
	v_fma_f32 v154, v154, v212, v146
	v_fma_f32 v155, v155, v213, v147
	v_fma_f32 v156, v156, v214, v148
	v_fma_f32 v157, v157, v215, v149
	v_fmac_f32_e32 v150, v86, v188
	v_fmac_f32_e32 v151, v87, v189
	v_fmac_f32_e32 v152, v88, v190
	v_fmac_f32_e32 v153, v89, v191
	v_fmac_f32_e32 v154, v82, v192
	v_fmac_f32_e32 v155, v83, v193
	v_fmac_f32_e32 v156, v84, v194
	v_fmac_f32_e32 v157, v85, v195
	v_cvt_pk_bf16_f32 v150, v150, v151
	v_cvt_pk_bf16_f32 v151, v152, v153
	v_cvt_pk_bf16_f32 v152, v154, v155
	v_cvt_pk_bf16_f32 v153, v156, v157
	s_add_u32 s38, s14, 0x90000
	s_addc_u32 s39, s15, 0
	global_store_dwordx4 v250, v[150:153], s[38:39] offset:0 sc0 sc1
	s_add_u32 s74, s14, 0x30000
	s_addc_u32 s75, s15, 0
	global_load_dwordx4 v[246:249], v250, s[74:75] offset:256
	s_nop 1
	s_waitcnt vmcnt(16)
	v_lshlrev_b32_e32 v150, 16, v122
	v_and_b32_e32 v151, 0xffff0000, v122
	v_lshlrev_b32_e32 v152, 16, v123
	v_and_b32_e32 v153, 0xffff0000, v123
	v_lshlrev_b32_e32 v154, 16, v124
	v_and_b32_e32 v155, 0xffff0000, v124
	v_lshlrev_b32_e32 v156, 16, v125
	v_and_b32_e32 v157, 0xffff0000, v125
	v_fma_f32 v150, v150, v185, v184
	v_fma_f32 v151, v151, v185, v184
	v_fma_f32 v152, v152, v185, v184
	v_fma_f32 v153, v153, v185, v184
	v_fma_f32 v154, v154, v185, v184
	v_fma_f32 v155, v155, v185, v184
	v_fma_f32 v156, v156, v185, v184
	v_fma_f32 v157, v157, v185, v184
	v_fma_f32 v150, v150, v208, v142
	v_fma_f32 v151, v151, v209, v143
	v_fma_f32 v152, v152, v210, v144
	v_fma_f32 v153, v153, v211, v145
	v_fma_f32 v154, v154, v212, v146
	v_fma_f32 v155, v155, v213, v147
	v_fma_f32 v156, v156, v214, v148
	v_fma_f32 v157, v157, v215, v149
	v_fmac_f32_e32 v150, v78, v188
	v_fmac_f32_e32 v151, v79, v189
	v_fmac_f32_e32 v152, v80, v190
	v_fmac_f32_e32 v153, v81, v191
	v_fmac_f32_e32 v154, v74, v192
	v_fmac_f32_e32 v155, v75, v193
	v_fmac_f32_e32 v156, v76, v194
	v_fmac_f32_e32 v157, v77, v195
	v_cvt_pk_bf16_f32 v150, v150, v151
	v_cvt_pk_bf16_f32 v151, v152, v153
	v_cvt_pk_bf16_f32 v152, v154, v155
	v_cvt_pk_bf16_f32 v153, v156, v157
	s_add_u32 s38, s14, 0xa0000
	s_addc_u32 s39, s15, 0
	global_store_dwordx4 v250, v[150:153], s[38:39] offset:0 sc0 sc1
	s_add_u32 s74, s14, 0x80000
	s_addc_u32 s75, s15, 0
	global_load_dwordx4 v[122:125], v250, s[74:75] offset:256
	s_nop 1
	s_waitcnt vmcnt(16)
	v_lshlrev_b32_e32 v150, 16, v126
	v_and_b32_e32 v151, 0xffff0000, v126
	v_lshlrev_b32_e32 v152, 16, v127
	v_and_b32_e32 v153, 0xffff0000, v127
	v_lshlrev_b32_e32 v154, 16, v128
	v_and_b32_e32 v155, 0xffff0000, v128
	v_lshlrev_b32_e32 v156, 16, v129
	v_and_b32_e32 v157, 0xffff0000, v129
	v_fma_f32 v150, v150, v187, v186
	v_fma_f32 v151, v151, v187, v186
	v_fma_f32 v152, v152, v187, v186
	v_fma_f32 v153, v153, v187, v186
	v_fma_f32 v154, v154, v187, v186
	v_fma_f32 v155, v155, v187, v186
	v_fma_f32 v156, v156, v187, v186
	v_fma_f32 v157, v157, v187, v186
	v_fma_f32 v150, v150, v208, v142
	v_fma_f32 v151, v151, v209, v143
	v_fma_f32 v152, v152, v210, v144
	v_fma_f32 v153, v153, v211, v145
	v_fma_f32 v154, v154, v212, v146
	v_fma_f32 v155, v155, v213, v147
	v_fma_f32 v156, v156, v214, v148
	v_fma_f32 v157, v157, v215, v149
	v_fmac_f32_e32 v150, v70, v188
	v_fmac_f32_e32 v151, v71, v189
	v_fmac_f32_e32 v152, v72, v190
	v_fmac_f32_e32 v153, v73, v191
	v_fmac_f32_e32 v154, v66, v192
	v_fmac_f32_e32 v155, v67, v193
	v_fmac_f32_e32 v156, v68, v194
	v_fmac_f32_e32 v157, v69, v195
	v_cvt_pk_bf16_f32 v150, v150, v151
	v_cvt_pk_bf16_f32 v151, v152, v153
	v_cvt_pk_bf16_f32 v152, v154, v155
	v_cvt_pk_bf16_f32 v153, v156, v157
	s_add_u32 s38, s14, 0xb0000
	s_addc_u32 s39, s15, 0
	global_store_dwordx4 v250, v[150:153], s[38:39] offset:0 sc0 sc1
	s_add_u32 s74, s14, 0x90000
	s_addc_u32 s75, s15, 0
	global_load_dwordx4 v[126:129], v250, s[74:75] offset:256
	s_nop 1
	s_waitcnt vmcnt(11)
	v_mul_f32_e32 v118, s16, v118
	v_mul_f32_e32 v110, s16, v110
	v_mul_f32_e32 v119, s16, v119
	v_mul_f32_e32 v111, s16, v111
	v_mul_f32_e32 v120, s16, v120
	v_mul_f32_e32 v112, s16, v112
	v_mul_f32_e32 v121, s16, v121
	v_mul_f32_e32 v113, s16, v113
	v_mul_f32_e32 v114, s16, v114
	v_mul_f32_e32 v106, s16, v106
	v_mul_f32_e32 v115, s16, v115
	v_mul_f32_e32 v107, s16, v107
	v_mul_f32_e32 v116, s16, v116
	v_mul_f32_e32 v108, s16, v108
	v_mul_f32_e32 v117, s16, v117
	v_mul_f32_e32 v109, s16, v109
	s_waitcnt vmcnt(10)
	v_lshlrev_b32_e32 v150, 16, v134
	v_and_b32_e32 v151, 0xffff0000, v134
	v_lshlrev_b32_e32 v152, 16, v135
	v_and_b32_e32 v153, 0xffff0000, v135
	v_lshlrev_b32_e32 v154, 16, v136
	v_and_b32_e32 v155, 0xffff0000, v136
	v_lshlrev_b32_e32 v156, 16, v137
	v_and_b32_e32 v157, 0xffff0000, v137
	v_fma_f32 v150, v150, v173, v172
	v_fma_f32 v151, v151, v173, v172
	v_fma_f32 v152, v152, v173, v172
	v_fma_f32 v153, v153, v173, v172
	v_fma_f32 v154, v154, v173, v172
	v_fma_f32 v155, v155, v173, v172
	v_fma_f32 v156, v156, v173, v172
	v_fma_f32 v157, v157, v173, v172
	v_fma_f32 v150, v150, v118, v110
	v_fma_f32 v151, v151, v119, v111
	v_fma_f32 v152, v152, v120, v112
	v_fma_f32 v153, v153, v121, v113
	v_fma_f32 v154, v154, v114, v106
	v_fma_f32 v155, v155, v115, v107
	v_fma_f32 v156, v156, v116, v108
	v_fma_f32 v157, v157, v117, v109
	v_fmac_f32_e32 v150, v62, v138
	v_fmac_f32_e32 v151, v63, v139
	v_fmac_f32_e32 v152, v64, v140
	v_fmac_f32_e32 v153, v65, v141
	v_fmac_f32_e32 v154, v58, v130
	v_fmac_f32_e32 v155, v59, v131
	v_fmac_f32_e32 v156, v60, v132
	v_fmac_f32_e32 v157, v61, v133
	v_cvt_pk_bf16_f32 v150, v150, v151
	v_cvt_pk_bf16_f32 v151, v152, v153
	v_cvt_pk_bf16_f32 v152, v154, v155
	v_cvt_pk_bf16_f32 v153, v156, v157
	global_store_dwordx4 v250, v[150:153], s[14:15] offset:256 sc0 sc1
	s_add_u32 s74, s14, 0xa0000
	s_addc_u32 s75, s15, 0
	global_load_dwordx4 v[134:137], v250, s[74:75] offset:256
	s_nop 1
	s_waitcnt vmcnt(10)
	v_lshlrev_b32_e32 v150, 16, v158
	v_and_b32_e32 v151, 0xffff0000, v158
	v_lshlrev_b32_e32 v152, 16, v159
	v_and_b32_e32 v153, 0xffff0000, v159
	v_lshlrev_b32_e32 v154, 16, v160
	v_and_b32_e32 v155, 0xffff0000, v160
	v_lshlrev_b32_e32 v156, 16, v161
	v_and_b32_e32 v157, 0xffff0000, v161
	v_fma_f32 v150, v150, v175, v174
	v_fma_f32 v151, v151, v175, v174
	v_fma_f32 v152, v152, v175, v174
	v_fma_f32 v153, v153, v175, v174
	v_fma_f32 v154, v154, v175, v174
	v_fma_f32 v155, v155, v175, v174
	v_fma_f32 v156, v156, v175, v174
	v_fma_f32 v157, v157, v175, v174
	v_fma_f32 v150, v150, v118, v110
	v_fma_f32 v151, v151, v119, v111
	v_fma_f32 v152, v152, v120, v112
	v_fma_f32 v153, v153, v121, v113
	v_fma_f32 v154, v154, v114, v106
	v_fma_f32 v155, v155, v115, v107
	v_fma_f32 v156, v156, v116, v108
	v_fma_f32 v157, v157, v117, v109
	v_fmac_f32_e32 v150, v54, v138
	v_fmac_f32_e32 v151, v55, v139
	v_fmac_f32_e32 v152, v56, v140
	v_fmac_f32_e32 v153, v57, v141
	v_fmac_f32_e32 v154, v50, v130
	v_fmac_f32_e32 v155, v51, v131
	v_fmac_f32_e32 v156, v52, v132
	v_fmac_f32_e32 v157, v53, v133
	v_cvt_pk_bf16_f32 v150, v150, v151
	v_cvt_pk_bf16_f32 v151, v152, v153
	v_cvt_pk_bf16_f32 v152, v154, v155
	v_cvt_pk_bf16_f32 v153, v156, v157
	s_add_u32 s38, s14, 0x10000
	s_addc_u32 s39, s15, 0
	global_store_dwordx4 v250, v[150:153], s[38:39] offset:256 sc0 sc1
	s_add_u32 s74, s14, 0xb0000
	s_addc_u32 s75, s15, 0
	global_load_dwordx4 v[158:161], v250, s[74:75] offset:256
	s_nop 1
	s_waitcnt vmcnt(10)
	v_lshlrev_b32_e32 v150, 16, v242
	v_and_b32_e32 v151, 0xffff0000, v242
	v_lshlrev_b32_e32 v152, 16, v243
	v_and_b32_e32 v153, 0xffff0000, v243
	v_lshlrev_b32_e32 v154, 16, v244
	v_and_b32_e32 v155, 0xffff0000, v244
	v_lshlrev_b32_e32 v156, 16, v245
	v_and_b32_e32 v157, 0xffff0000, v245
	v_fma_f32 v150, v150, v177, v176
	v_fma_f32 v151, v151, v177, v176
	v_fma_f32 v152, v152, v177, v176
	v_fma_f32 v153, v153, v177, v176
	v_fma_f32 v154, v154, v177, v176
	v_fma_f32 v155, v155, v177, v176
	v_fma_f32 v156, v156, v177, v176
	v_fma_f32 v157, v157, v177, v176
	v_fma_f32 v150, v150, v118, v110
	v_fma_f32 v151, v151, v119, v111
	v_fma_f32 v152, v152, v120, v112
	v_fma_f32 v153, v153, v121, v113
	v_fma_f32 v154, v154, v114, v106
	v_fma_f32 v155, v155, v115, v107
	v_fma_f32 v156, v156, v116, v108
	v_fma_f32 v157, v157, v117, v109
	v_fmac_f32_e32 v150, v46, v138
	v_fmac_f32_e32 v151, v47, v139
	v_fmac_f32_e32 v152, v48, v140
	v_fmac_f32_e32 v153, v49, v141
	v_fmac_f32_e32 v154, v42, v130
	v_fmac_f32_e32 v155, v43, v131
	v_fmac_f32_e32 v156, v44, v132
	v_fmac_f32_e32 v157, v45, v133
	v_cvt_pk_bf16_f32 v150, v150, v151
	v_cvt_pk_bf16_f32 v151, v152, v153
	v_cvt_pk_bf16_f32 v152, v154, v155
	v_cvt_pk_bf16_f32 v153, v156, v157
	s_add_u32 s38, s14, 0x20000
	s_addc_u32 s39, s15, 0
	global_store_dwordx4 v250, v[150:153], s[38:39] offset:256 sc0 sc1
	s_nop 1
	s_waitcnt vmcnt(9)
	v_lshlrev_b32_e32 v150, 16, v246
	v_and_b32_e32 v151, 0xffff0000, v246
	v_lshlrev_b32_e32 v152, 16, v247
	v_and_b32_e32 v153, 0xffff0000, v247
	v_lshlrev_b32_e32 v154, 16, v248
	v_and_b32_e32 v155, 0xffff0000, v248
	v_lshlrev_b32_e32 v156, 16, v249
	v_and_b32_e32 v157, 0xffff0000, v249
	v_fma_f32 v150, v150, v179, v178
	v_fma_f32 v151, v151, v179, v178
	v_fma_f32 v152, v152, v179, v178
	v_fma_f32 v153, v153, v179, v178
	v_fma_f32 v154, v154, v179, v178
	v_fma_f32 v155, v155, v179, v178
	v_fma_f32 v156, v156, v179, v178
	v_fma_f32 v157, v157, v179, v178
	v_fma_f32 v150, v150, v118, v110
	v_fma_f32 v151, v151, v119, v111
	v_fma_f32 v152, v152, v120, v112
	v_fma_f32 v153, v153, v121, v113
	v_fma_f32 v154, v154, v114, v106
	v_fma_f32 v155, v155, v115, v107
	v_fma_f32 v156, v156, v116, v108
	v_fma_f32 v157, v157, v117, v109
	v_fmac_f32_e32 v150, v38, v138
	v_fmac_f32_e32 v151, v39, v139
	v_fmac_f32_e32 v152, v40, v140
	v_fmac_f32_e32 v153, v41, v141
	v_fmac_f32_e32 v154, v34, v130
	v_fmac_f32_e32 v155, v35, v131
	v_fmac_f32_e32 v156, v36, v132
	v_fmac_f32_e32 v157, v37, v133
	v_cvt_pk_bf16_f32 v150, v150, v151
	v_cvt_pk_bf16_f32 v151, v152, v153
	v_cvt_pk_bf16_f32 v152, v154, v155
	v_cvt_pk_bf16_f32 v153, v156, v157
	s_add_u32 s38, s14, 0x30000
	s_addc_u32 s39, s15, 0
	global_store_dwordx4 v250, v[150:153], s[38:39] offset:256 sc0 sc1
	s_nop 1
	s_waitcnt vmcnt(8)
	v_lshlrev_b32_e32 v150, 16, v122
	v_and_b32_e32 v151, 0xffff0000, v122
	v_lshlrev_b32_e32 v152, 16, v123
	v_and_b32_e32 v153, 0xffff0000, v123
	v_lshlrev_b32_e32 v154, 16, v124
	v_and_b32_e32 v155, 0xffff0000, v124
	v_lshlrev_b32_e32 v156, 16, v125
	v_and_b32_e32 v157, 0xffff0000, v125
	v_fma_f32 v150, v150, v181, v180
	v_fma_f32 v151, v151, v181, v180
	v_fma_f32 v152, v152, v181, v180
	v_fma_f32 v153, v153, v181, v180
	v_fma_f32 v154, v154, v181, v180
	v_fma_f32 v155, v155, v181, v180
	v_fma_f32 v156, v156, v181, v180
	v_fma_f32 v157, v157, v181, v180
	v_fma_f32 v150, v150, v118, v110
	v_fma_f32 v151, v151, v119, v111
	v_fma_f32 v152, v152, v120, v112
	v_fma_f32 v153, v153, v121, v113
	v_fma_f32 v154, v154, v114, v106
	v_fma_f32 v155, v155, v115, v107
	v_fma_f32 v156, v156, v116, v108
	v_fma_f32 v157, v157, v117, v109
	v_fmac_f32_e32 v150, v30, v138
	v_fmac_f32_e32 v151, v31, v139
	v_fmac_f32_e32 v152, v32, v140
	v_fmac_f32_e32 v153, v33, v141
	v_fmac_f32_e32 v154, v26, v130
	v_fmac_f32_e32 v155, v27, v131
	v_fmac_f32_e32 v156, v28, v132
	v_fmac_f32_e32 v157, v29, v133
	v_cvt_pk_bf16_f32 v150, v150, v151
	v_cvt_pk_bf16_f32 v151, v152, v153
	v_cvt_pk_bf16_f32 v152, v154, v155
	v_cvt_pk_bf16_f32 v153, v156, v157
	s_add_u32 s38, s14, 0x80000
	s_addc_u32 s39, s15, 0
	global_store_dwordx4 v250, v[150:153], s[38:39] offset:256 sc0 sc1
	s_nop 1
	s_waitcnt vmcnt(7)
	v_lshlrev_b32_e32 v150, 16, v126
	v_and_b32_e32 v151, 0xffff0000, v126
	v_lshlrev_b32_e32 v152, 16, v127
	v_and_b32_e32 v153, 0xffff0000, v127
	v_lshlrev_b32_e32 v154, 16, v128
	v_and_b32_e32 v155, 0xffff0000, v128
	v_lshlrev_b32_e32 v156, 16, v129
	v_and_b32_e32 v157, 0xffff0000, v129
	v_fma_f32 v150, v150, v183, v182
	v_fma_f32 v151, v151, v183, v182
	v_fma_f32 v152, v152, v183, v182
	v_fma_f32 v153, v153, v183, v182
	v_fma_f32 v154, v154, v183, v182
	v_fma_f32 v155, v155, v183, v182
	v_fma_f32 v156, v156, v183, v182
	v_fma_f32 v157, v157, v183, v182
	v_fma_f32 v150, v150, v118, v110
	v_fma_f32 v151, v151, v119, v111
	v_fma_f32 v152, v152, v120, v112
	v_fma_f32 v153, v153, v121, v113
	v_fma_f32 v154, v154, v114, v106
	v_fma_f32 v155, v155, v115, v107
	v_fma_f32 v156, v156, v116, v108
	v_fma_f32 v157, v157, v117, v109
	v_fmac_f32_e32 v150, v22, v138
	v_fmac_f32_e32 v151, v23, v139
	v_fmac_f32_e32 v152, v24, v140
	v_fmac_f32_e32 v153, v25, v141
	v_fmac_f32_e32 v154, v18, v130
	v_fmac_f32_e32 v155, v19, v131
	v_fmac_f32_e32 v156, v20, v132
	v_fmac_f32_e32 v157, v21, v133
	v_cvt_pk_bf16_f32 v150, v150, v151
	v_cvt_pk_bf16_f32 v151, v152, v153
	v_cvt_pk_bf16_f32 v152, v154, v155
	v_cvt_pk_bf16_f32 v153, v156, v157
	s_add_u32 s38, s14, 0x90000
	s_addc_u32 s39, s15, 0
	global_store_dwordx4 v250, v[150:153], s[38:39] offset:256 sc0 sc1
	s_nop 1
	s_waitcnt vmcnt(6)
	v_lshlrev_b32_e32 v150, 16, v134
	v_and_b32_e32 v151, 0xffff0000, v134
	v_lshlrev_b32_e32 v152, 16, v135
	v_and_b32_e32 v153, 0xffff0000, v135
	v_lshlrev_b32_e32 v154, 16, v136
	v_and_b32_e32 v155, 0xffff0000, v136
	v_lshlrev_b32_e32 v156, 16, v137
	v_and_b32_e32 v157, 0xffff0000, v137
	v_fma_f32 v150, v150, v185, v184
	v_fma_f32 v151, v151, v185, v184
	v_fma_f32 v152, v152, v185, v184
	v_fma_f32 v153, v153, v185, v184
	v_fma_f32 v154, v154, v185, v184
	v_fma_f32 v155, v155, v185, v184
	v_fma_f32 v156, v156, v185, v184
	v_fma_f32 v157, v157, v185, v184
	v_fma_f32 v150, v150, v118, v110
	v_fma_f32 v151, v151, v119, v111
	v_fma_f32 v152, v152, v120, v112
	v_fma_f32 v153, v153, v121, v113
	v_fma_f32 v154, v154, v114, v106
	v_fma_f32 v155, v155, v115, v107
	v_fma_f32 v156, v156, v116, v108
	v_fma_f32 v157, v157, v117, v109
	v_fmac_f32_e32 v150, v14, v138
	v_fmac_f32_e32 v151, v15, v139
	v_fmac_f32_e32 v152, v16, v140
	v_fmac_f32_e32 v153, v17, v141
	v_fmac_f32_e32 v154, v10, v130
	v_fmac_f32_e32 v155, v11, v131
	v_fmac_f32_e32 v156, v12, v132
	v_fmac_f32_e32 v157, v13, v133
	v_cvt_pk_bf16_f32 v150, v150, v151
	v_cvt_pk_bf16_f32 v151, v152, v153
	v_cvt_pk_bf16_f32 v152, v154, v155
	v_cvt_pk_bf16_f32 v153, v156, v157
	s_add_u32 s38, s14, 0xa0000
	s_addc_u32 s39, s15, 0
	global_store_dwordx4 v250, v[150:153], s[38:39] offset:256 sc0 sc1
	s_nop 1
	s_waitcnt vmcnt(5)
	v_lshlrev_b32_e32 v150, 16, v158
	v_and_b32_e32 v151, 0xffff0000, v158
	v_lshlrev_b32_e32 v152, 16, v159
	v_and_b32_e32 v153, 0xffff0000, v159
	v_lshlrev_b32_e32 v154, 16, v160
	v_and_b32_e32 v155, 0xffff0000, v160
	v_lshlrev_b32_e32 v156, 16, v161
	v_and_b32_e32 v157, 0xffff0000, v161
	v_fma_f32 v150, v150, v187, v186
	v_fma_f32 v151, v151, v187, v186
	v_fma_f32 v152, v152, v187, v186
	v_fma_f32 v153, v153, v187, v186
	v_fma_f32 v154, v154, v187, v186
	v_fma_f32 v155, v155, v187, v186
	v_fma_f32 v156, v156, v187, v186
	v_fma_f32 v157, v157, v187, v186
	v_fma_f32 v150, v150, v118, v110
	v_fma_f32 v151, v151, v119, v111
	v_fma_f32 v152, v152, v120, v112
	v_fma_f32 v153, v153, v121, v113
	v_fma_f32 v154, v154, v114, v106
	v_fma_f32 v155, v155, v115, v107
	v_fma_f32 v156, v156, v116, v108
	v_fma_f32 v157, v157, v117, v109
	v_fmac_f32_e32 v150, v6, v138
	v_fmac_f32_e32 v151, v7, v139
	v_fmac_f32_e32 v152, v8, v140
	v_fmac_f32_e32 v153, v9, v141
	v_fmac_f32_e32 v154, v2, v130
	v_fmac_f32_e32 v155, v3, v131
	v_fmac_f32_e32 v156, v4, v132
	v_fmac_f32_e32 v157, v5, v133
	v_cvt_pk_bf16_f32 v150, v150, v151
	v_cvt_pk_bf16_f32 v151, v152, v153
	v_cvt_pk_bf16_f32 v152, v154, v155
	v_cvt_pk_bf16_f32 v153, v156, v157
	s_add_u32 s38, s14, 0xb0000
	s_addc_u32 s39, s15, 0
	global_store_dwordx4 v250, v[150:153], s[38:39] offset:256 sc0 sc1
	s_nop 1
	s_branch .Lres_done
.Lres_xpath:
	global_load_dwordx4 v[188:191], v251, s[6:7]
	global_load_dwordx4 v[192:195], v251, s[6:7] offset:16
	v_readlane_b32 s16, v252, 41
	v_readlane_b32 s17, v252, 42
	v_readlane_b32 s18, v253, 38
	v_readlane_b32 s19, v253, 39
	s_cmp_lt_i32 s9, 32
	s_cselect_b32 s16, s16, s18
	s_cselect_b32 s17, s17, s19
	s_lshl_b32 s5, s4, 13
	s_add_u32 s16, s16, s5
	s_addc_u32 s17, s17, 0
	s_add_u32 s16, s16, s41
	s_addc_u32 s17, s17, 0
	s_lshl_b32 s5, s4, 12
	s_add_u32 s14, s0, s5
	s_addc_u32 s15, s1, 0
	s_lshl_b32 s5, s40, 1
	s_add_u32 s14, s14, s5
	s_addc_u32 s15, s15, 0
	v_lshlrev_b32_e32 v250, 13, v238
	v_lshl_or_b32 v250, v237, 5, v250
	v_lshlrev_b32_e32 v197, 12, v238
	v_lshl_or_b32 v197, v237, 4, v197
	global_load_dwordx4 v[122:125], v250, s[16:17] offset:0
	global_load_dwordx4 v[126:129], v250, s[16:17] offset:16
	s_add_u32 s74, s16, 0x20000
	s_addc_u32 s75, s17, 0
	global_load_dwordx4 v[142:145], v250, s[74:75] offset:0
	global_load_dwordx4 v[146:149], v250, s[74:75] offset:16
	s_add_u32 s74, s16, 0x40000
	s_addc_u32 s75, s17, 0
	global_load_dwordx4 v[150:153], v250, s[74:75] offset:0
	global_load_dwordx4 v[154:157], v250, s[74:75] offset:16
	s_add_u32 s74, s16, 0x60000
	s_addc_u32 s75, s17, 0
	global_load_dwordx4 v[172:175], v250, s[74:75] offset:0
	global_load_dwordx4 v[176:179], v250, s[74:75] offset:16
	s_add_u32 s74, s16, 0x100000
	s_addc_u32 s75, s17, 0
	global_load_dwordx4 v[180:183], v250, s[74:75] offset:0
	global_load_dwordx4 v[184:187], v250, s[74:75] offset:16
	s_add_u32 s74, s16, 0x120000
	s_addc_u32 s75, s17, 0
	global_load_dwordx4 v[208:211], v250, s[74:75] offset:0
	global_load_dwordx4 v[212:215], v250, s[74:75] offset:16
	s_add_u32 s74, s16, 0x140000
	s_addc_u32 s75, s17, 0
	global_load_dwordx4 v[242:245], v250, s[74:75] offset:0
	global_load_dwordx4 v[246:249], v250, s[74:75] offset:16
	s_add_u32 s74, s16, 0x160000
	s_addc_u32 s75, s17, 0
	global_load_dwordx4 v[134:137], v250, s[74:75] offset:0
	global_load_dwordx4 v[158:161], v250, s[74:75] offset:16
	s_mov_b32 s18, 0x3fb504f3
	s_waitcnt vmcnt(16)
	s_waitcnt vmcnt(14)
	v_mul_f32_e32 v122, s18, v122
	v_mul_f32_e32 v123, s18, v123
	v_mul_f32_e32 v124, s18, v124
	v_mul_f32_e32 v125, s18, v125
	v_mul_f32_e32 v126, s18, v126
	v_mul_f32_e32 v127, s18, v127
	v_mul_f32_e32 v128, s18, v128
	v_mul_f32_e32 v129, s18, v129
	v_fmac_f32_e32 v122, v138, v188
	v_fmac_f32_e32 v123, v139, v189
	v_fmac_f32_e32 v124, v140, v190
	v_fmac_f32_e32 v125, v141, v191
	v_fmac_f32_e32 v126, v130, v192
	v_fmac_f32_e32 v127, v131, v193
	v_fmac_f32_e32 v128, v132, v194
	v_fmac_f32_e32 v129, v133, v195
	v_cvt_pk_bf16_f32 v122, v122, v123
	v_cvt_pk_bf16_f32 v123, v124, v125
	v_cvt_pk_bf16_f32 v124, v126, v127
	v_cvt_pk_bf16_f32 v125, v128, v129
	global_store_dwordx4 v197, v[122:125], s[14:15] offset:0 sc0 sc1
	global_load_dwordx4 v[138:141], v251, s[6:7] offset:512
	global_load_dwordx4 v[130:133], v251, s[6:7] offset:528
	s_nop 1
	global_load_dwordx4 v[122:125], v250, s[16:17] offset:512
	global_load_dwordx4 v[126:129], v250, s[16:17] offset:528
	s_waitcnt vmcnt(17)
	v_mul_f32_e32 v142, s18, v142
	v_mul_f32_e32 v143, s18, v143
	v_mul_f32_e32 v144, s18, v144
	v_mul_f32_e32 v145, s18, v145
	v_mul_f32_e32 v146, s18, v146
	v_mul_f32_e32 v147, s18, v147
	v_mul_f32_e32 v148, s18, v148
	v_mul_f32_e32 v149, s18, v149
	v_fmac_f32_e32 v142, v118, v188
	v_fmac_f32_e32 v143, v119, v189
	v_fmac_f32_e32 v144, v120, v190
	v_fmac_f32_e32 v145, v121, v191
	v_fmac_f32_e32 v146, v114, v192
	v_fmac_f32_e32 v147, v115, v193
	v_fmac_f32_e32 v148, v116, v194
	v_fmac_f32_e32 v149, v117, v195
	v_cvt_pk_bf16_f32 v142, v142, v143
	v_cvt_pk_bf16_f32 v143, v144, v145
	v_cvt_pk_bf16_f32 v144, v146, v147
	v_cvt_pk_bf16_f32 v145, v148, v149
	s_add_u32 s38, s14, 0x10000
	s_addc_u32 s39, s15, 0
	global_store_dwordx4 v197, v[142:145], s[38:39] offset:0 sc0 sc1
	s_nop 1
	s_add_u32 s74, s16, 0x20000
	s_addc_u32 s75, s17, 0
	global_load_dwordx4 v[142:145], v250, s[74:75] offset:512
	global_load_dwordx4 v[146:149], v250, s[74:75] offset:528
	s_waitcnt vmcnt(18)
	v_mul_f32_e32 v150, s18, v150
	v_mul_f32_e32 v151, s18, v151
	v_mul_f32_e32 v152, s18, v152
	v_mul_f32_e32 v153, s18, v153
	v_mul_f32_e32 v154, s18, v154
	v_mul_f32_e32 v155, s18, v155
	v_mul_f32_e32 v156, s18, v156
	v_mul_f32_e32 v157, s18, v157
	v_fmac_f32_e32 v150, v110, v188
	v_fmac_f32_e32 v151, v111, v189
	v_fmac_f32_e32 v152, v112, v190
	v_fmac_f32_e32 v153, v113, v191
	v_fmac_f32_e32 v154, v106, v192
	v_fmac_f32_e32 v155, v107, v193
	v_fmac_f32_e32 v156, v108, v194
	v_fmac_f32_e32 v157, v109, v195
	v_cvt_pk_bf16_f32 v150, v150, v151
	v_cvt_pk_bf16_f32 v151, v152, v153
	v_cvt_pk_bf16_f32 v152, v154, v155
	v_cvt_pk_bf16_f32 v153, v156, v157
	s_add_u32 s38, s14, 0x20000
	s_addc_u32 s39, s15, 0
	global_store_dwordx4 v197, v[150:153], s[38:39] offset:0 sc0 sc1
	s_nop 1
	s_add_u32 s74, s16, 0x40000
	s_addc_u32 s75, s17, 0
	global_load_dwordx4 v[150:153], v250, s[74:75] offset:512
	global_load_dwordx4 v[154:157], v250, s[74:75] offset:528
	s_waitcnt vmcnt(19)
	v_mul_f32_e32 v172, s18, v172
	v_mul_f32_e32 v173, s18, v173
	v_mul_f32_e32 v174, s18, v174
	v_mul_f32_e32 v175, s18, v175
	v_mul_f32_e32 v176, s18, v176
	v_mul_f32_e32 v177, s18, v177
	v_mul_f32_e32 v178, s18, v178
	v_mul_f32_e32 v179, s18, v179
	v_fmac_f32_e32 v172, v102, v188
	v_fmac_f32_e32 v173, v103, v189
	v_fmac_f32_e32 v174, v104, v190
	v_fmac_f32_e32 v175, v105, v191
	v_fmac_f32_e32 v176, v98, v192
	v_fmac_f32_e32 v177, v99, v193
	v_fmac_f32_e32 v178, v100, v194
	v_fmac_f32_e32 v179, v101, v195
	v_cvt_pk_bf16_f32 v172, v172, v173
	v_cvt_pk_bf16_f32 v173, v174, v175
	v_cvt_pk_bf16_f32 v174, v176, v177
	v_cvt_pk_bf16_f32 v175, v178, v179
	s_add_u32 s38, s14, 0x30000
	s_addc_u32 s39, s15, 0
	global_store_dwordx4 v197, v[172:175], s[38:39] offset:0 sc0 sc1
	s_nop 1
	s_add_u32 s74, s16, 0x60000
	s_addc_u32 s75, s17, 0
	global_load_dwordx4 v[172:175], v250, s[74:75] offset:512
	global_load_dwordx4 v[176:179], v250, s[74:75] offset:528
	s_waitcnt vmcnt(20)
	v_mul_f32_e32 v180, s18, v180
	v_mul_f32_e32 v181, s18, v181
	v_mul_f32_e32 v182, s18, v182
	v_mul_f32_e32 v183, s18, v183
	v_mul_f32_e32 v184, s18, v184
	v_mul_f32_e32 v185, s18, v185
	v_mul_f32_e32 v186, s18, v186
	v_mul_f32_e32 v187, s18, v187
	v_fmac_f32_e32 v180, v94, v188
	v_fmac_f32_e32 v181, v95, v189
	v_fmac_f32_e32 v182, v96, v190
	v_fmac_f32_e32 v183, v97, v191
	v_fmac_f32_e32 v184, v90, v192
	v_fmac_f32_e32 v185, v91, v193
	v_fmac_f32_e32 v186, v92, v194
	v_fmac_f32_e32 v187, v93, v195
	v_cvt_pk_bf16_f32 v180, v180, v181
	v_cvt_pk_bf16_f32 v181, v182, v183
	v_cvt_pk_bf16_f32 v182, v184, v185
	v_cvt_pk_bf16_f32 v183, v186, v187
	s_add_u32 s38, s14, 0x80000
	s_addc_u32 s39, s15, 0
	global_store_dwordx4 v197, v[180:183], s[38:39] offset:0 sc0 sc1
	s_nop 1
	s_add_u32 s74, s16, 0x100000
	s_addc_u32 s75, s17, 0
	global_load_dwordx4 v[180:183], v250, s[74:75] offset:512
	global_load_dwordx4 v[184:187], v250, s[74:75] offset:528
	s_waitcnt vmcnt(21)
	v_mul_f32_e32 v208, s18, v208
	v_mul_f32_e32 v209, s18, v209
	v_mul_f32_e32 v210, s18, v210
	v_mul_f32_e32 v211, s18, v211
	v_mul_f32_e32 v212, s18, v212
	v_mul_f32_e32 v213, s18, v213
	v_mul_f32_e32 v214, s18, v214
	v_mul_f32_e32 v215, s18, v215
	v_fmac_f32_e32 v208, v86, v188
	v_fmac_f32_e32 v209, v87, v189
	v_fmac_f32_e32 v210, v88, v190
	v_fmac_f32_e32 v211, v89, v191
	v_fmac_f32_e32 v212, v82, v192
	v_fmac_f32_e32 v213, v83, v193
	v_fmac_f32_e32 v214, v84, v194
	v_fmac_f32_e32 v215, v85, v195
	v_cvt_pk_bf16_f32 v208, v208, v209
	v_cvt_pk_bf16_f32 v209, v210, v211
	v_cvt_pk_bf16_f32 v210, v212, v213
	v_cvt_pk_bf16_f32 v211, v214, v215
	s_add_u32 s38, s14, 0x90000
	s_addc_u32 s39, s15, 0
	global_store_dwordx4 v197, v[208:211], s[38:39] offset:0 sc0 sc1
	s_nop 1
	s_add_u32 s74, s16, 0x120000
	s_addc_u32 s75, s17, 0
	global_load_dwordx4 v[208:211], v250, s[74:75] offset:512
	global_load_dwordx4 v[212:215], v250, s[74:75] offset:528
	s_waitcnt vmcnt(22)
	v_mul_f32_e32 v242, s18, v242
	v_mul_f32_e32 v243, s18, v243
	v_mul_f32_e32 v244, s18, v244
	v_mul_f32_e32 v245, s18, v245
	v_mul_f32_e32 v246, s18, v246
	v_mul_f32_e32 v247, s18, v247
	v_mul_f32_e32 v248, s18, v248
	v_mul_f32_e32 v249, s18, v249
	v_fmac_f32_e32 v242, v78, v188
	v_fmac_f32_e32 v243, v79, v189
	v_fmac_f32_e32 v244, v80, v190
	v_fmac_f32_e32 v245, v81, v191
	v_fmac_f32_e32 v246, v74, v192
	v_fmac_f32_e32 v247, v75, v193
	v_fmac_f32_e32 v248, v76, v194
	v_fmac_f32_e32 v249, v77, v195
	v_cvt_pk_bf16_f32 v242, v242, v243
	v_cvt_pk_bf16_f32 v243, v244, v245
	v_cvt_pk_bf16_f32 v244, v246, v247
	v_cvt_pk_bf16_f32 v245, v248, v249
	s_add_u32 s38, s14, 0xa0000
	s_addc_u32 s39, s15, 0
	global_store_dwordx4 v197, v[242:245], s[38:39] offset:0 sc0 sc1
	s_nop 1
	s_add_u32 s74, s16, 0x140000
	s_addc_u32 s75, s17, 0
	global_load_dwordx4 v[242:245], v250, s[74:75] offset:512
	global_load_dwordx4 v[246:249], v250, s[74:75] offset:528
	s_waitcnt vmcnt(23)
	v_mul_f32_e32 v134, s18, v134
	v_mul_f32_e32 v135, s18, v135
	v_mul_f32_e32 v136, s18, v136
	v_mul_f32_e32 v137, s18, v137
	v_mul_f32_e32 v158, s18, v158
	v_mul_f32_e32 v159, s18, v159
	v_mul_f32_e32 v160, s18, v160
	v_mul_f32_e32 v161, s18, v161
	v_fmac_f32_e32 v134, v70, v188
	v_fmac_f32_e32 v135, v71, v189
	v_fmac_f32_e32 v136, v72, v190
	v_fmac_f32_e32 v137, v73, v191
	v_fmac_f32_e32 v158, v66, v192
	v_fmac_f32_e32 v159, v67, v193
	v_fmac_f32_e32 v160, v68, v194
	v_fmac_f32_e32 v161, v69, v195
	v_cvt_pk_bf16_f32 v134, v134, v135
	v_cvt_pk_bf16_f32 v135, v136, v137
	v_cvt_pk_bf16_f32 v136, v158, v159
	v_cvt_pk_bf16_f32 v137, v160, v161
	s_add_u32 s38, s14, 0xb0000
	s_addc_u32 s39, s15, 0
	global_store_dwordx4 v197, v[134:137], s[38:39] offset:0 sc0 sc1
	s_nop 1
	s_add_u32 s74, s16, 0x160000
	s_addc_u32 s75, s17, 0
	global_load_dwordx4 v[134:137], v250, s[74:75] offset:512
	global_load_dwordx4 v[158:161], v250, s[74:75] offset:528
	s_waitcnt vmcnt(23)
	s_waitcnt vmcnt(21)
	v_mul_f32_e32 v122, s18, v122
	v_mul_f32_e32 v123, s18, v123
	v_mul_f32_e32 v124, s18, v124
	v_mul_f32_e32 v125, s18, v125
	v_mul_f32_e32 v126, s18, v126
	v_mul_f32_e32 v127, s18, v127
	v_mul_f32_e32 v128, s18, v128
	v_mul_f32_e32 v129, s18, v129
	v_fmac_f32_e32 v122, v62, v138
	v_fmac_f32_e32 v123, v63, v139
	v_fmac_f32_e32 v124, v64, v140
	v_fmac_f32_e32 v125, v65, v141
	v_fmac_f32_e32 v126, v58, v130
	v_fmac_f32_e32 v127, v59, v131
	v_fmac_f32_e32 v128, v60, v132
	v_fmac_f32_e32 v129, v61, v133
	v_cvt_pk_bf16_f32 v122, v122, v123
	v_cvt_pk_bf16_f32 v123, v124, v125
	v_cvt_pk_bf16_f32 v124, v126, v127
	v_cvt_pk_bf16_f32 v125, v128, v129
	global_store_dwordx4 v197, v[122:125], s[14:15] offset:256 sc0 sc1
	s_nop 1
	s_waitcnt vmcnt(19)
	v_mul_f32_e32 v142, s18, v142
	v_mul_f32_e32 v143, s18, v143
	v_mul_f32_e32 v144, s18, v144
	v_mul_f32_e32 v145, s18, v145
	v_mul_f32_e32 v146, s18, v146
	v_mul_f32_e32 v147, s18, v147
	v_mul_f32_e32 v148, s18, v148
	v_mul_f32_e32 v149, s18, v149
	v_fmac_f32_e32 v142, v54, v138
	v_fmac_f32_e32 v143, v55, v139
	v_fmac_f32_e32 v144, v56, v140
	v_fmac_f32_e32 v145, v57, v141
	v_fmac_f32_e32 v146, v50, v130
	v_fmac_f32_e32 v147, v51, v131
	v_fmac_f32_e32 v148, v52, v132
	v_fmac_f32_e32 v149, v53, v133
	v_cvt_pk_bf16_f32 v142, v142, v143
	v_cvt_pk_bf16_f32 v143, v144, v145
	v_cvt_pk_bf16_f32 v144, v146, v147
	v_cvt_pk_bf16_f32 v145, v148, v149
	s_add_u32 s38, s14, 0x10000
	s_addc_u32 s39, s15, 0
	global_store_dwordx4 v197, v[142:145], s[38:39] offset:256 sc0 sc1
	s_nop 1
	s_waitcnt vmcnt(17)
	v_mul_f32_e32 v150, s18, v150
	v_mul_f32_e32 v151, s18, v151
	v_mul_f32_e32 v152, s18, v152
	v_mul_f32_e32 v153, s18, v153
	v_mul_f32_e32 v154, s18, v154
	v_mul_f32_e32 v155, s18, v155
	v_mul_f32_e32 v156, s18, v156
	v_mul_f32_e32 v157, s18, v157
	v_fmac_f32_e32 v150, v46, v138
	v_fmac_f32_e32 v151, v47, v139
	v_fmac_f32_e32 v152, v48, v140
	v_fmac_f32_e32 v153, v49, v141
	v_fmac_f32_e32 v154, v42, v130
	v_fmac_f32_e32 v155, v43, v131
	v_fmac_f32_e32 v156, v44, v132
	v_fmac_f32_e32 v157, v45, v133
	v_cvt_pk_bf16_f32 v150, v150, v151
	v_cvt_pk_bf16_f32 v151, v152, v153
	v_cvt_pk_bf16_f32 v152, v154, v155
	v_cvt_pk_bf16_f32 v153, v156, v157
	s_add_u32 s38, s14, 0x20000
	s_addc_u32 s39, s15, 0
	global_store_dwordx4 v197, v[150:153], s[38:39] offset:256 sc0 sc1
	s_nop 1
	s_waitcnt vmcnt(15)
	v_mul_f32_e32 v172, s18, v172
	v_mul_f32_e32 v173, s18, v173
	v_mul_f32_e32 v174, s18, v174
	v_mul_f32_e32 v175, s18, v175
	v_mul_f32_e32 v176, s18, v176
	v_mul_f32_e32 v177, s18, v177
	v_mul_f32_e32 v178, s18, v178
	v_mul_f32_e32 v179, s18, v179
	v_fmac_f32_e32 v172, v38, v138
	v_fmac_f32_e32 v173, v39, v139
	v_fmac_f32_e32 v174, v40, v140
	v_fmac_f32_e32 v175, v41, v141
	v_fmac_f32_e32 v176, v34, v130
	v_fmac_f32_e32 v177, v35, v131
	v_fmac_f32_e32 v178, v36, v132
	v_fmac_f32_e32 v179, v37, v133
	v_cvt_pk_bf16_f32 v172, v172, v173
	v_cvt_pk_bf16_f32 v173, v174, v175
	v_cvt_pk_bf16_f32 v174, v176, v177
	v_cvt_pk_bf16_f32 v175, v178, v179
	s_add_u32 s38, s14, 0x30000
	s_addc_u32 s39, s15, 0
	global_store_dwordx4 v197, v[172:175], s[38:39] offset:256 sc0 sc1
	s_nop 1
	s_waitcnt vmcnt(13)
	v_mul_f32_e32 v180, s18, v180
	v_mul_f32_e32 v181, s18, v181
	v_mul_f32_e32 v182, s18, v182
	v_mul_f32_e32 v183, s18, v183
	v_mul_f32_e32 v184, s18, v184
	v_mul_f32_e32 v185, s18, v185
	v_mul_f32_e32 v186, s18, v186
	v_mul_f32_e32 v187, s18, v187
	v_fmac_f32_e32 v180, v30, v138
	v_fmac_f32_e32 v181, v31, v139
	v_fmac_f32_e32 v182, v32, v140
	v_fmac_f32_e32 v183, v33, v141
	v_fmac_f32_e32 v184, v26, v130
	v_fmac_f32_e32 v185, v27, v131
	v_fmac_f32_e32 v186, v28, v132
	v_fmac_f32_e32 v187, v29, v133
	v_cvt_pk_bf16_f32 v180, v180, v181
	v_cvt_pk_bf16_f32 v181, v182, v183
	v_cvt_pk_bf16_f32 v182, v184, v185
	v_cvt_pk_bf16_f32 v183, v186, v187
	s_add_u32 s38, s14, 0x80000
	s_addc_u32 s39, s15, 0
	global_store_dwordx4 v197, v[180:183], s[38:39] offset:256 sc0 sc1
	s_nop 1
	s_waitcnt vmcnt(11)
	v_mul_f32_e32 v208, s18, v208
	v_mul_f32_e32 v209, s18, v209
	v_mul_f32_e32 v210, s18, v210
	v_mul_f32_e32 v211, s18, v211
	v_mul_f32_e32 v212, s18, v212
	v_mul_f32_e32 v213, s18, v213
	v_mul_f32_e32 v214, s18, v214
	v_mul_f32_e32 v215, s18, v215
	v_fmac_f32_e32 v208, v22, v138
	v_fmac_f32_e32 v209, v23, v139
	v_fmac_f32_e32 v210, v24, v140
	v_fmac_f32_e32 v211, v25, v141
	v_fmac_f32_e32 v212, v18, v130
	v_fmac_f32_e32 v213, v19, v131
	v_fmac_f32_e32 v214, v20, v132
	v_fmac_f32_e32 v215, v21, v133
	v_cvt_pk_bf16_f32 v208, v208, v209
	v_cvt_pk_bf16_f32 v209, v210, v211
	v_cvt_pk_bf16_f32 v210, v212, v213
	v_cvt_pk_bf16_f32 v211, v214, v215
	s_add_u32 s38, s14, 0x90000
	s_addc_u32 s39, s15, 0
	global_store_dwordx4 v197, v[208:211], s[38:39] offset:256 sc0 sc1
	s_nop 1
	s_waitcnt vmcnt(9)
	v_mul_f32_e32 v242, s18, v242
	v_mul_f32_e32 v243, s18, v243
	v_mul_f32_e32 v244, s18, v244
	v_mul_f32_e32 v245, s18, v245
	v_mul_f32_e32 v246, s18, v246
	v_mul_f32_e32 v247, s18, v247
	v_mul_f32_e32 v248, s18, v248
	v_mul_f32_e32 v249, s18, v249
	v_fmac_f32_e32 v242, v14, v138
	v_fmac_f32_e32 v243, v15, v139
	v_fmac_f32_e32 v244, v16, v140
	v_fmac_f32_e32 v245, v17, v141
	v_fmac_f32_e32 v246, v10, v130
	v_fmac_f32_e32 v247, v11, v131
	v_fmac_f32_e32 v248, v12, v132
	v_fmac_f32_e32 v249, v13, v133
	v_cvt_pk_bf16_f32 v242, v242, v243
	v_cvt_pk_bf16_f32 v243, v244, v245
	v_cvt_pk_bf16_f32 v244, v246, v247
	v_cvt_pk_bf16_f32 v245, v248, v249
	s_add_u32 s38, s14, 0xa0000
	s_addc_u32 s39, s15, 0
	global_store_dwordx4 v197, v[242:245], s[38:39] offset:256 sc0 sc1
	s_nop 1
	s_waitcnt vmcnt(7)
	v_mul_f32_e32 v134, s18, v134
	v_mul_f32_e32 v135, s18, v135
	v_mul_f32_e32 v136, s18, v136
	v_mul_f32_e32 v137, s18, v137
	v_mul_f32_e32 v158, s18, v158
	v_mul_f32_e32 v159, s18, v159
	v_mul_f32_e32 v160, s18, v160
	v_mul_f32_e32 v161, s18, v161
	v_fmac_f32_e32 v134, v6, v138
	v_fmac_f32_e32 v135, v7, v139
	v_fmac_f32_e32 v136, v8, v140
	v_fmac_f32_e32 v137, v9, v141
	v_fmac_f32_e32 v158, v2, v130
	v_fmac_f32_e32 v159, v3, v131
	v_fmac_f32_e32 v160, v4, v132
	v_fmac_f32_e32 v161, v5, v133
	v_cvt_pk_bf16_f32 v134, v134, v135
	v_cvt_pk_bf16_f32 v135, v136, v137
	v_cvt_pk_bf16_f32 v136, v158, v159
	v_cvt_pk_bf16_f32 v137, v160, v161
	s_add_u32 s38, s14, 0xb0000
	s_addc_u32 s39, s15, 0
	global_store_dwordx4 v197, v[134:137], s[38:39] offset:256 sc0 sc1
	s_nop 1
